# P0a: nt on the once-read f32 weight tile loads, on top of P6 residual nt
# speedup vs baseline: 1.0046x; 1.0035x over previous
.LBB0_18:
	s_lshl_b32 s11, s8, 1
	s_lshl_b32 s10, s7, 1
	v_or_b32_e32 v34, s11, v4
	s_add_i32 s27, s11, 4
	v_mov_b32_e32 v7, v35
	v_or_b32_e32 v6, s10, v5
	s_add_i32 s26, s10, 4
	s_add_i32 s37, s11, 8
	v_lshlrev_b64 v[22:23], 14, v[34:35]
	v_or_b32_e32 v34, s27, v4
	v_mov_b32_e32 v9, v35
	s_add_i32 s36, s10, 8
	s_add_i32 s45, s11, 12
	v_lshlrev_b64 v[6:7], 14, v[6:7]
	v_or_b32_e32 v8, s26, v5
	v_lshlrev_b64 v[24:25], 14, v[34:35]
	v_or_b32_e32 v34, s37, v4
	v_mov_b32_e32 v11, v35
	s_add_i32 s44, s10, 12
	s_add_i32 s49, s11, 16
	v_or_b32_e32 v10, s36, v5
	v_lshl_add_u64 v[22:23], v[2:3], 0, v[22:23]
	v_lshl_add_u64 v[6:7], v[2:3], 0, v[6:7]
	v_lshlrev_b64 v[8:9], 14, v[8:9]
	v_lshl_add_u64 v[24:25], v[2:3], 0, v[24:25]
	v_lshlrev_b64 v[26:27], 14, v[34:35]
	v_or_b32_e32 v34, s45, v4
	v_mov_b32_e32 v13, v35
	s_add_i32 s47, s10, 16
	s_add_i32 s50, s10, 20
	s_add_i32 s51, s11, 20
	v_or_b32_e32 v12, s44, v5
	v_lshlrev_b64 v[10:11], 14, v[10:11]
	v_lshl_add_u64 v[8:9], v[2:3], 0, v[8:9]
	global_load_dword v22, v[22:23], off nt
	s_nop 0
	global_load_dword v23, v[6:7], off nt
	s_nop 0
	global_load_dword v6, v[24:25], off nt
	global_load_dword v7, v[8:9], off nt
	v_lshlrev_b64 v[24:25], 14, v[34:35]
	v_or_b32_e32 v34, s49, v4
	v_mov_b32_e32 v15, v35
	v_mov_b32_e32 v17, v35
	s_add_i32 s52, s10, 24
	s_add_i32 s53, s11, 24
	v_or_b32_e32 v14, s47, v5
	v_or_b32_e32 v16, s50, v5
	v_lshlrev_b64 v[12:13], 14, v[12:13]
	v_lshl_add_u64 v[10:11], v[2:3], 0, v[10:11]
	v_lshl_add_u64 v[8:9], v[2:3], 0, v[26:27]
	v_lshl_add_u64 v[24:25], v[2:3], 0, v[24:25]
	v_lshlrev_b64 v[26:27], 14, v[34:35]
	v_or_b32_e32 v34, s51, v4
	v_mov_b32_e32 v19, v35
	s_add_i32 s55, s11, 28
	v_or_b32_e32 v18, s52, v5
	v_lshlrev_b64 v[14:15], 14, v[14:15]
	v_lshlrev_b64 v[16:17], 14, v[16:17]
	v_lshl_add_u64 v[12:13], v[2:3], 0, v[12:13]
	global_load_dword v8, v[8:9], off nt
	s_nop 0
	global_load_dword v9, v[10:11], off nt
	s_nop 0
	global_load_dword v10, v[24:25], off nt
	global_load_dword v11, v[12:13], off nt
	v_lshlrev_b64 v[24:25], 14, v[34:35]
	v_or_b32_e32 v34, s53, v4
	s_add_i32 s54, s10, 28
	v_lshlrev_b64 v[18:19], 14, v[18:19]
	v_lshl_add_u64 v[14:15], v[2:3], 0, v[14:15]
	v_lshl_add_u64 v[16:17], v[2:3], 0, v[16:17]
	v_lshl_add_u64 v[12:13], v[2:3], 0, v[26:27]
	v_lshl_add_u64 v[24:25], v[2:3], 0, v[24:25]
	v_lshlrev_b64 v[26:27], 14, v[34:35]
	v_or_b32_e32 v34, s55, v4
	v_mov_b32_e32 v21, v35
	v_or_b32_e32 v20, s54, v5
	v_lshl_add_u64 v[18:19], v[2:3], 0, v[18:19]
	global_load_dword v12, v[12:13], off nt
	s_nop 0
	global_load_dword v13, v[14:15], off nt
	s_nop 0
	global_load_dword v14, v[24:25], off nt
	global_load_dword v15, v[16:17], off nt
	v_lshl_add_u64 v[16:17], v[2:3], 0, v[26:27]
	v_lshlrev_b64 v[24:25], 14, v[34:35]
	v_lshlrev_b64 v[20:21], 14, v[20:21]
	global_load_dword v16, v[16:17], off nt
	s_nop 0
	global_load_dword v17, v[18:19], off nt
	v_lshl_add_u64 v[18:19], v[2:3], 0, v[24:25]
	v_lshl_add_u64 v[20:21], v[2:3], 0, v[20:21]
	global_load_dword v18, v[18:19], off nt
	s_nop 0
	global_load_dword v19, v[20:21], off nt
	v_or_b32_e32 v24, s10, v1
	v_or_b32_e32 v20, s11, v38
	v_mad_u64_u32 v[24:25], s[10:11], v24, s21, v[44:45]
	v_mad_u64_u32 v[20:21], s[10:11], v20, s21, v[44:45]
	v_or_b32_e32 v25, s27, v38
	v_or_b32_e32 v21, s26, v1
	v_or_b32_e32 v30, s37, v38
	v_mad_u64_u32 v[26:27], s[10:11], v25, s21, v[44:45]
	v_or_b32_e32 v32, s36, v1
	v_or_b32_e32 v61, s45, v38
	v_mad_u64_u32 v[28:29], s[10:11], v21, s21, v[44:45]
	v_mad_u64_u32 v[30:31], s[10:11], v30, s21, v[44:45]
	v_or_b32_e32 v34, s44, v1
	v_or_b32_e32 v84, s49, v38
	v_mad_u64_u32 v[32:33], s[10:11], v32, s21, v[44:45]
	v_mad_u64_u32 v[80:81], s[10:11], v61, s21, v[44:45]
	v_or_b32_e32 v79, s47, v1
	v_or_b32_e32 v88, s51, v38
	v_mad_u64_u32 v[82:83], s[10:11], v34, s21, v[44:45]
	v_mad_u64_u32 v[84:85], s[10:11], v84, s21, v[44:45]
	v_or_b32_e32 v90, s50, v1
	v_or_b32_e32 v92, s53, v38
	v_mad_u64_u32 v[86:87], s[10:11], v79, s21, v[44:45]
	v_mad_u64_u32 v[88:89], s[10:11], v88, s21, v[44:45]
	s_waitcnt vmcnt(14)
	v_pk_mul_f32 v[22:23], v[22:23], s[20:21] op_sel_hi:[1,0]
	ds_write_b32 v20, v22
	ds_write_b32 v24, v23
	s_waitcnt vmcnt(12)
	v_pk_mul_f32 v[6:7], v[6:7], s[20:21] op_sel_hi:[1,0]
	ds_write_b32 v26, v6
	ds_write_b32 v28, v7
	s_add_i32 s8, s8, 16
	s_add_i32 s7, s7, 16
	s_add_i32 s9, s9, -16
	v_or_b32_e32 v94, s52, v1
	v_or_b32_e32 v96, s55, v38
	v_mad_u64_u32 v[90:91], s[10:11], v90, s21, v[44:45]
	v_mad_u64_u32 v[92:93], s[10:11], v92, s21, v[44:45]
	v_or_b32_e32 v98, s54, v1
	s_cmp_lg_u32 s9, 0
	v_mad_u64_u32 v[94:95], s[10:11], v94, s21, v[44:45]
	v_mad_u64_u32 v[96:97], s[10:11], v96, s21, v[44:45]
	v_mad_u64_u32 v[98:99], s[10:11], v98, s21, v[44:45]
	s_waitcnt vmcnt(10)
	v_pk_mul_f32 v[6:7], v[8:9], s[20:21] op_sel_hi:[1,0]
	ds_write_b32 v30, v6
	ds_write_b32 v32, v7
	s_waitcnt vmcnt(8)
	v_pk_mul_f32 v[6:7], v[10:11], s[20:21] op_sel_hi:[1,0]
	ds_write_b32 v80, v6
	ds_write_b32 v82, v7
	s_waitcnt vmcnt(6)
	v_pk_mul_f32 v[6:7], v[12:13], s[20:21] op_sel_hi:[1,0]
	ds_write_b32 v84, v6
	ds_write_b32 v86, v7
	s_waitcnt vmcnt(4)
	v_pk_mul_f32 v[6:7], v[14:15], s[20:21] op_sel_hi:[1,0]
	ds_write_b32 v88, v6
	ds_write_b32 v90, v7
	s_waitcnt vmcnt(2)
	v_pk_mul_f32 v[6:7], v[16:17], s[20:21] op_sel_hi:[1,0]
	ds_write_b32 v92, v6
	ds_write_b32 v94, v7
	s_waitcnt vmcnt(0)
	v_pk_mul_f32 v[6:7], v[18:19], s[20:21] op_sel_hi:[1,0]
	ds_write_b32 v96, v6
	ds_write_b32 v98, v7
	s_cbranch_scc1 .LBB0_18
	s_waitcnt lgkmcnt(0)
	ds_read2_b32 v[6:7], v59 offset1:16
	ds_read2_b32 v[8:9], v59 offset0:33 offset1:49
	ds_read2_b32 v[10:11], v59 offset0:66 offset1:82
	ds_read2_b32 v[12:13], v59 offset0:99 offset1:115
	ds_read2_b32 v[16:17], v59 offset0:132 offset1:148
	ds_read2_b32 v[18:19], v59 offset0:165 offset1:181
	ds_read2_b32 v[20:21], v59 offset0:198 offset1:214
	ds_read2_b32 v[22:23], v59 offset0:231 offset1:247
	s_waitcnt lgkmcnt(7)
	v_max_f32_e32 v2, v6, v6
	s_waitcnt lgkmcnt(6)
	v_max_f32_e32 v3, v8, v8
	v_med3_f32 v6, v2, s39, v77
	v_med3_f32 v3, v3, s39, v77
	v_mov_b32_e32 v2, v35
	v_cvt_pk_fp8_f32 v2, v6, v3
	s_waitcnt lgkmcnt(5)
	v_max_f32_e32 v4, v10, v10
	s_waitcnt lgkmcnt(4)
	v_max_f32_e32 v5, v12, v12
	v_med3_f32 v4, v4, s39, v77
	v_med3_f32 v5, v5, s39, v77
	v_cvt_pk_fp8_f32 v2, v4, v5 op_sel:[0,0,1]
	s_waitcnt lgkmcnt(3)
	v_max_f32_e32 v3, v16, v16
	s_waitcnt lgkmcnt(2)
	v_max_f32_e32 v4, v18, v18
	v_med3_f32 v8, v3, s39, v77
	v_med3_f32 v4, v4, s39, v77
	v_mov_b32_e32 v3, v35
	v_cvt_pk_fp8_f32 v3, v8, v4
	v_add_u32_e32 v8, 0x400, v59
	ds_read2_b32 v[24:25], v8 offset0:8 offset1:24
	ds_read2_b32 v[26:27], v8 offset0:41 offset1:57
	ds_read2_b32 v[28:29], v8 offset0:74 offset1:90
	ds_read2_b32 v[30:31], v8 offset0:107 offset1:123
	s_waitcnt lgkmcnt(5)
	v_max_f32_e32 v5, v20, v20
	s_waitcnt lgkmcnt(4)
	v_max_f32_e32 v6, v22, v22
	v_med3_f32 v5, v5, s39, v77
	v_med3_f32 v6, v6, s39, v77
	v_cvt_pk_fp8_f32 v3, v5, v6 op_sel:[0,0,1]
	s_waitcnt lgkmcnt(3)
	v_max_f32_e32 v4, v24, v24
	s_waitcnt lgkmcnt(2)
	v_max_f32_e32 v5, v26, v26
	v_med3_f32 v12, v4, s39, v77
	v_med3_f32 v5, v5, s39, v77
	v_mov_b32_e32 v4, v35
	v_cvt_pk_fp8_f32 v4, v12, v5
	ds_read2_b32 v[32:33], v8 offset0:140 offset1:156
	ds_read2_b32 v[80:81], v8 offset0:173 offset1:189
	ds_read2_b32 v[82:83], v8 offset0:206 offset1:222
	s_waitcnt lgkmcnt(4)
	v_max_f32_e32 v6, v28, v28
	s_waitcnt lgkmcnt(3)
	v_max_f32_e32 v10, v30, v30
	v_med3_f32 v6, v6, s39, v77
	v_med3_f32 v5, v10, s39, v77
	ds_read2_b32 v[84:85], v8 offset0:239 offset1:255
	v_cvt_pk_fp8_f32 v4, v6, v5 op_sel:[0,0,1]
	s_waitcnt lgkmcnt(3)
	v_max_f32_e32 v5, v32, v32
	s_waitcnt lgkmcnt(2)
	v_max_f32_e32 v6, v80, v80
	v_med3_f32 v8, v5, s39, v77
	v_med3_f32 v6, v6, s39, v77
	v_mov_b32_e32 v5, v35
	v_cvt_pk_fp8_f32 v5, v8, v6
	s_waitcnt lgkmcnt(1)
	v_max_f32_e32 v10, v82, v82
	s_waitcnt lgkmcnt(0)
	v_max_f32_e32 v6, v84, v84
	v_med3_f32 v8, v10, s39, v77
	v_med3_f32 v6, v6, s39, v77
	v_cvt_pk_fp8_f32 v5, v8, v6 op_sel:[0,0,1]
	v_or_b32_e32 v6, s6, v45
	v_lshl_add_u64 v[14:15], v[46:47], 0, s[16:17]
	v_lshlrev_b32_e32 v34, 14, v6
	v_lshl_add_u64 v[86:87], v[14:15], 0, v[34:35]
	global_store_dwordx4 v[86:87], v[2:5], off
	s_nop 1
	v_max_f32_e32 v2, v7, v7
	v_max_f32_e32 v3, v9, v9
	v_med3_f32 v5, v2, s39, v77
	v_med3_f32 v3, v3, s39, v77
	v_mov_b32_e32 v2, v35
	v_cvt_pk_fp8_f32 v2, v5, v3
	v_max_f32_e32 v4, v11, v11
	v_max_f32_e32 v3, v13, v13
	v_med3_f32 v4, v4, s39, v77
	v_med3_f32 v3, v3, s39, v77
	v_cvt_pk_fp8_f32 v2, v4, v3 op_sel:[0,0,1]
	v_max_f32_e32 v3, v17, v17
	v_max_f32_e32 v4, v19, v19
	v_med3_f32 v6, v3, s39, v77
	v_med3_f32 v4, v4, s39, v77
	v_mov_b32_e32 v3, v35
	v_cvt_pk_fp8_f32 v3, v6, v4
	v_max_f32_e32 v5, v21, v21
	v_max_f32_e32 v4, v23, v23
	v_med3_f32 v5, v5, s39, v77
	v_med3_f32 v4, v4, s39, v77
	v_cvt_pk_fp8_f32 v3, v5, v4 op_sel:[0,0,1]
	v_max_f32_e32 v4, v25, v25
	v_max_f32_e32 v5, v27, v27
	v_med3_f32 v7, v4, s39, v77
	v_med3_f32 v5, v5, s39, v77
	v_mov_b32_e32 v4, v35
	v_cvt_pk_fp8_f32 v4, v7, v5
	v_max_f32_e32 v6, v29, v29
	v_max_f32_e32 v5, v31, v31
	v_med3_f32 v6, v6, s39, v77
	v_med3_f32 v5, v5, s39, v77
	v_cvt_pk_fp8_f32 v4, v6, v5 op_sel:[0,0,1]
	v_max_f32_e32 v5, v33, v33
	v_max_f32_e32 v6, v81, v81
	v_med3_f32 v8, v5, s39, v77
	v_med3_f32 v6, v6, s39, v77
	v_mov_b32_e32 v5, v35
	v_cvt_pk_fp8_f32 v5, v8, v6
	v_max_f32_e32 v7, v83, v83
	v_max_f32_e32 v6, v85, v85
	v_med3_f32 v7, v7, s39, v77
	v_med3_f32 v6, v6, s39, v77
	v_cvt_pk_fp8_f32 v5, v7, v6 op_sel:[0,0,1]
	v_or_b32_e32 v6, s6, v62
	v_lshlrev_b32_e32 v34, 14, v6
	v_lshl_add_u64 v[6:7], v[14:15], 0, v[34:35]
	global_store_dwordx4 v[6:7], v[2:5], off
	s_waitcnt lgkmcnt(0)
	s_mov_b64 s[6:7], 0

.LBB0_22:
	s_lshl_b32 s11, s8, 1
	s_lshl_b32 s16, s9, 1
	v_or_b32_e32 v34, s16, v4
	s_add_i32 s36, s11, 4
	s_add_i32 s37, s16, 4
	v_mov_b32_e32 v9, v35
	s_add_i32 s45, s16, 8
	v_lshlrev_b64 v[22:23], 16, v[34:35]
	v_or_b32_e32 v8, s36, v5
	v_or_b32_e32 v34, s37, v4
	v_mov_b32_e32 v7, v35
	v_or_b32_e32 v6, s11, v5
	s_add_i32 s49, s16, 12
	v_lshlrev_b64 v[8:9], 16, v[8:9]
	v_lshlrev_b64 v[24:25], 16, v[34:35]
	v_or_b32_e32 v34, s45, v4
	s_add_i32 s44, s11, 8
	s_add_i32 s47, s11, 12
	s_add_i32 s51, s16, 16
	v_lshlrev_b64 v[6:7], 16, v[6:7]
	v_lshl_add_u64 v[22:23], v[2:3], 0, v[22:23]
	v_lshl_add_u64 v[8:9], v[2:3], 0, v[8:9]
	v_lshlrev_b64 v[26:27], 16, v[34:35]
	v_or_b32_e32 v34, s49, v4
	v_mov_b32_e32 v11, v35
	v_mov_b32_e32 v13, v35
	s_add_i32 s53, s16, 20
	v_or_b32_e32 v10, s44, v5
	v_or_b32_e32 v12, s47, v5
	v_lshl_add_u64 v[6:7], v[2:3], 0, v[6:7]
	v_lshl_add_u64 v[24:25], v[2:3], 0, v[24:25]
	global_load_dword v61, v[22:23], off nt
	global_load_dword v79, v[6:7], off nt
	global_load_dword v84, v[24:25], off nt
	global_load_dword v85, v[8:9], off nt
	v_lshlrev_b64 v[8:9], 16, v[34:35]
	v_or_b32_e32 v34, s51, v4
	s_add_i32 s50, s11, 16
	s_add_i32 s52, s11, 20
	s_add_i32 s55, s16, 24
	v_lshlrev_b64 v[10:11], 16, v[10:11]
	v_lshlrev_b64 v[12:13], 16, v[12:13]
	v_lshl_add_u64 v[6:7], v[2:3], 0, v[26:27]
	v_lshl_add_u64 v[8:9], v[2:3], 0, v[8:9]
	v_lshlrev_b64 v[22:23], 16, v[34:35]
	v_or_b32_e32 v34, s53, v4
	v_mov_b32_e32 v15, v35
	v_mov_b32_e32 v17, v35
	s_add_i32 s54, s11, 24
	s_add_i32 s56, s11, 28
	s_add_i32 s57, s16, 28
	v_or_b32_e32 v14, s50, v5
	v_or_b32_e32 v16, s52, v5
	v_lshl_add_u64 v[10:11], v[2:3], 0, v[10:11]
	v_lshl_add_u64 v[12:13], v[2:3], 0, v[12:13]
	global_load_dword v86, v[6:7], off nt
	global_load_dword v87, v[10:11], off nt
	global_load_dword v88, v[8:9], off nt
	global_load_dword v89, v[12:13], off nt
	v_lshlrev_b64 v[8:9], 16, v[34:35]
	v_or_b32_e32 v34, s55, v4
	v_mov_b32_e32 v19, v35
	v_mov_b32_e32 v21, v35
	v_or_b32_e32 v18, s54, v5
	v_or_b32_e32 v20, s56, v5
	v_lshlrev_b64 v[14:15], 16, v[14:15]
	v_lshlrev_b64 v[16:17], 16, v[16:17]
	v_lshl_add_u64 v[6:7], v[2:3], 0, v[22:23]
	v_lshl_add_u64 v[8:9], v[2:3], 0, v[8:9]
	v_lshlrev_b64 v[10:11], 16, v[34:35]
	v_or_b32_e32 v34, s57, v4
	v_lshlrev_b64 v[18:19], 16, v[18:19]
	v_lshlrev_b64 v[20:21], 16, v[20:21]
	v_lshl_add_u64 v[14:15], v[2:3], 0, v[14:15]
	v_lshl_add_u64 v[16:17], v[2:3], 0, v[16:17]
	global_load_dword v90, v[6:7], off nt
	global_load_dword v91, v[14:15], off nt
	global_load_dword v92, v[8:9], off nt
	global_load_dword v93, v[16:17], off nt
	v_lshl_add_u64 v[6:7], v[2:3], 0, v[10:11]
	v_lshlrev_b64 v[8:9], 16, v[34:35]
	v_lshl_add_u64 v[18:19], v[2:3], 0, v[18:19]
	v_lshl_add_u64 v[20:21], v[2:3], 0, v[20:21]
	v_lshl_add_u64 v[8:9], v[2:3], 0, v[8:9]
	global_load_dword v34, v[6:7], off nt
	global_load_dword v94, v[18:19], off nt
	global_load_dword v95, v[8:9], off nt
	global_load_dword v96, v[20:21], off nt
	v_or_b32_e32 v8, s11, v1
	v_or_b32_e32 v6, s16, v38
	s_add_i32 s9, s9, 16
	s_add_i32 s8, s8, 16
	s_add_i32 s10, s10, -16
	v_mad_u64_u32 v[6:7], s[26:27], v6, s21, v[44:45]
	v_mad_u64_u32 v[8:9], s[26:27], v8, s21, v[44:45]
	v_or_b32_e32 v7, s36, v1
	v_or_b32_e32 v9, s37, v38
	v_or_b32_e32 v16, s44, v1
	v_or_b32_e32 v14, s45, v38
	v_or_b32_e32 v20, s47, v1
	v_or_b32_e32 v18, s49, v38
	v_or_b32_e32 v24, s50, v1
	v_or_b32_e32 v22, s51, v38
	v_or_b32_e32 v28, s52, v1
	v_or_b32_e32 v26, s53, v38
	v_or_b32_e32 v32, s54, v1
	v_or_b32_e32 v30, s55, v38
	v_or_b32_e32 v82, s56, v1
	v_or_b32_e32 v80, s57, v38
	s_cmp_lg_u32 s10, 0
	v_mad_u64_u32 v[10:11], s[26:27], v9, s21, v[44:45]
	v_mad_u64_u32 v[12:13], s[26:27], v7, s21, v[44:45]
	v_mad_u64_u32 v[14:15], s[26:27], v14, s21, v[44:45]
	v_mad_u64_u32 v[16:17], s[26:27], v16, s21, v[44:45]
	v_mad_u64_u32 v[18:19], s[26:27], v18, s21, v[44:45]
	v_mad_u64_u32 v[20:21], s[26:27], v20, s21, v[44:45]
	v_mad_u64_u32 v[22:23], s[26:27], v22, s21, v[44:45]
	v_mad_u64_u32 v[24:25], s[26:27], v24, s21, v[44:45]
	v_mad_u64_u32 v[26:27], s[26:27], v26, s21, v[44:45]
	v_mad_u64_u32 v[28:29], s[26:27], v28, s21, v[44:45]
	v_mad_u64_u32 v[30:31], s[26:27], v30, s21, v[44:45]
	v_mad_u64_u32 v[32:33], s[26:27], v32, s21, v[44:45]
	v_mad_u64_u32 v[80:81], s[26:27], v80, s21, v[44:45]
	v_mad_u64_u32 v[82:83], s[26:27], v82, s21, v[44:45]
	s_waitcnt vmcnt(15)
	ds_write_b32 v6, v61
	s_waitcnt vmcnt(14)
	ds_write_b32 v8, v79
	s_waitcnt vmcnt(13)
	ds_write_b32 v10, v84
	s_waitcnt vmcnt(12)
	ds_write_b32 v12, v85
	s_waitcnt vmcnt(11)
	ds_write_b32 v14, v86
	s_waitcnt vmcnt(10)
	ds_write_b32 v16, v87
	s_waitcnt vmcnt(9)
	ds_write_b32 v18, v88
	s_waitcnt vmcnt(8)
	ds_write_b32 v20, v89
	s_waitcnt vmcnt(7)
	ds_write_b32 v22, v90
	s_waitcnt vmcnt(6)
	ds_write_b32 v24, v91
	s_waitcnt vmcnt(5)
	ds_write_b32 v26, v92
	s_waitcnt vmcnt(4)
	ds_write_b32 v28, v93
	s_waitcnt vmcnt(3)
	ds_write_b32 v30, v34
	s_waitcnt vmcnt(2)
	ds_write_b32 v32, v94
	s_waitcnt vmcnt(1)
	ds_write_b32 v80, v95
	s_waitcnt vmcnt(0)
	ds_write_b32 v82, v96
	s_cbranch_scc1 .LBB0_22
	s_waitcnt lgkmcnt(0)
	ds_read2_b32 v[2:3], v63 offset1:33
	v_add_u32_e32 v16, 0x800, v63
	v_add_u32_e32 v18, 0x400, v63
	v_add_u32_e32 v19, 0xc00, v63
	ds_read2_b32 v[4:5], v16 offset0:16 offset1:49
	ds_read2_b32 v[6:7], v63 offset0:66 offset1:99
	ds_read2_b32 v[8:9], v16 offset0:82 offset1:115
	ds_read2_b32 v[10:11], v63 offset0:132 offset1:165
	ds_read2_b32 v[12:13], v16 offset0:148 offset1:181
	ds_read2_b32 v[14:15], v63 offset0:198 offset1:231
	ds_read2_b32 v[16:17], v16 offset0:214 offset1:247
	ds_read2_b32 v[26:27], v18 offset0:8 offset1:41
	ds_read2_b32 v[28:29], v19 offset0:24 offset1:57
	ds_read2_b32 v[30:31], v18 offset0:74 offset1:107
	ds_read2_b32 v[32:33], v19 offset0:90 offset1:123
	ds_read2_b32 v[80:81], v18 offset0:140 offset1:173
	ds_read2_b32 v[82:83], v19 offset0:156 offset1:189
	ds_read2_b32 v[84:85], v18 offset0:206 offset1:239
	ds_read2_b32 v[86:87], v19 offset0:222 offset1:255
	s_waitcnt lgkmcnt(14)
	v_max_f32_e64 v18, |v4|, |v4|
	v_max_f32_e64 v19, |v2|, |v2|
	v_max_f32_e32 v18, v19, v18
	v_max_f32_e64 v19, |v5|, |v5|
	v_max_f32_e64 v20, |v3|, |v3|
	v_max_f32_e32 v19, v20, v19
	v_max3_f32 v18, v18, 0, v19
	s_waitcnt lgkmcnt(12)
	v_max_f32_e64 v19, |v8|, |v8|
	v_max_f32_e64 v20, |v6|, |v6|
	v_max_f32_e32 v19, v20, v19
	v_max_f32_e64 v20, |v9|, |v9|
	v_max_f32_e64 v21, |v7|, |v7|
	v_max_f32_e32 v20, v21, v20
	v_max3_f32 v18, v18, v19, v20
	s_waitcnt lgkmcnt(10)
	v_max_f32_e64 v19, |v12|, |v12|
	v_max_f32_e64 v20, |v10|, |v10|
	v_max_f32_e32 v19, v20, v19
	v_max_f32_e64 v20, |v13|, |v13|
	v_max_f32_e64 v21, |v11|, |v11|
	v_max_f32_e32 v20, v21, v20
	v_max3_f32 v18, v18, v19, v20
	s_waitcnt lgkmcnt(8)
	v_max_f32_e64 v19, |v16|, |v16|
	v_max_f32_e64 v20, |v14|, |v14|
	v_max_f32_e32 v19, v20, v19
	v_max_f32_e64 v20, |v17|, |v17|
	v_max_f32_e64 v21, |v15|, |v15|
	v_max_f32_e32 v20, v21, v20
	v_max3_f32 v18, v18, v19, v20
	s_waitcnt lgkmcnt(6)
	v_max_f32_e64 v19, |v28|, |v28|
	v_max_f32_e64 v20, |v26|, |v26|
	v_max_f32_e32 v19, v20, v19
	v_max_f32_e64 v20, |v29|, |v29|
	v_max_f32_e64 v21, |v27|, |v27|
	v_max_f32_e32 v20, v21, v20
	v_max3_f32 v18, v18, v19, v20
	s_waitcnt lgkmcnt(4)
	v_max_f32_e64 v19, |v32|, |v32|
	v_max_f32_e64 v20, |v30|, |v30|
	v_max_f32_e32 v19, v20, v19
	v_max_f32_e64 v20, |v33|, |v33|
	v_max_f32_e64 v21, |v31|, |v31|
	v_max_f32_e32 v20, v21, v20
	v_max3_f32 v18, v18, v19, v20
	s_waitcnt lgkmcnt(2)
	v_max_f32_e64 v19, |v82|, |v82|
	v_max_f32_e64 v20, |v80|, |v80|
	v_max_f32_e32 v19, v20, v19
	v_max_f32_e64 v20, |v83|, |v83|
	v_max_f32_e64 v21, |v81|, |v81|
	v_max_f32_e32 v20, v21, v20
	v_max3_f32 v18, v18, v19, v20
	s_waitcnt lgkmcnt(0)
	v_max_f32_e64 v19, |v86|, |v86|
	v_max_f32_e64 v20, |v84|, |v84|
	v_max_f32_e32 v19, v20, v19
	v_max_f32_e64 v20, |v87|, |v87|
	v_max_f32_e64 v21, |v85|, |v85|
	v_max_f32_e32 v20, v21, v20
	v_max3_f32 v18, v18, v19, v20
	v_bfe_u32 v18, v18, 23, 8
	v_max_u32_e32 v34, 3, v18
	v_lshlrev_b32_e32 v18, 23, v34
	v_sub_u32_e32 v61, 0x80000000, v18
	v_mul_f32_e32 v4, v4, v61
	v_med3_f32 v18, v4, s40, v78
	v_mul_f32_e32 v4, v5, v61
	v_mul_f32_e32 v5, v8, v61
	v_med3_f32 v19, v4, s40, v78
	v_mul_f32_e32 v4, v6, v61
	v_med3_f32 v20, v5, s40, v78
	v_mul_f32_e32 v5, v7, v61
	v_mul_f32_e32 v6, v9, v61
	v_mul_f32_e32 v7, v12, v61
	v_mul_f32_e32 v8, v13, v61
	v_mul_f32_e32 v9, v16, v61
	v_med3_f32 v21, v6, s40, v78
	v_mul_f32_e32 v6, v10, v61
	v_med3_f32 v22, v7, s40, v78
	v_mul_f32_e32 v7, v11, v61
	v_med3_f32 v23, v8, s40, v78
	v_mul_f32_e32 v8, v14, v61
	v_med3_f32 v24, v9, s40, v78
	v_mul_f32_e32 v9, v15, v61
	v_mul_f32_e32 v10, v17, v61
	v_mul_f32_e32 v11, v28, v61
	v_mul_f32_e32 v12, v29, v61
	v_mul_f32_e32 v13, v32, v61
	v_mul_f32_e32 v14, v33, v61
	v_mul_f32_e32 v15, v82, v61
	v_mul_f32_e32 v16, v83, v61
	v_mul_f32_e32 v17, v86, v61
	v_mul_f32_e32 v2, v2, v61
	v_mul_f32_e32 v3, v3, v61
	v_med3_f32 v25, v10, s40, v78
	v_mul_f32_e32 v10, v26, v61
	v_med3_f32 v26, v11, s40, v78
	v_mul_f32_e32 v11, v27, v61
	v_med3_f32 v27, v12, s40, v78
	v_mul_f32_e32 v12, v30, v61
	v_med3_f32 v28, v13, s40, v78
	v_mul_f32_e32 v13, v31, v61
	v_med3_f32 v29, v14, s40, v78
	v_mul_f32_e32 v14, v80, v61
	v_med3_f32 v30, v15, s40, v78
	v_mul_f32_e32 v15, v81, v61
	v_med3_f32 v31, v16, s40, v78
	v_mul_f32_e32 v16, v84, v61
	v_med3_f32 v32, v17, s40, v78
	v_mul_f32_e32 v17, v85, v61
	v_mul_f32_e32 v33, v87, v61
	v_med3_f32 v2, v2, s40, v78
	v_med3_f32 v3, v3, s40, v78
	v_med3_f32 v4, v4, s40, v78
	v_med3_f32 v5, v5, s40, v78
	v_med3_f32 v6, v6, s40, v78
	v_med3_f32 v7, v7, s40, v78
	v_med3_f32 v8, v8, s40, v78
	v_med3_f32 v9, v9, s40, v78
	v_med3_f32 v10, v10, s40, v78
	v_med3_f32 v11, v11, s40, v78
	v_med3_f32 v12, v12, s40, v78
	v_med3_f32 v13, v13, s40, v78
	v_med3_f32 v14, v14, s40, v78
	v_med3_f32 v15, v15, s40, v78
	v_med3_f32 v16, v16, s40, v78
	v_med3_f32 v17, v17, s40, v78
	v_med3_f32 v33, v33, s40, v78
	s_and_b32 s7, 0xffff, s7
	v_cvt_scalef32_2xpk16_fp6_f32 v[2:7], v[2:17], v[18:33], 1.0
	v_mov_b32_e32 v32, v6
	v_or_b32_e32 v6, s7, v40
	v_mov_b32_e32 v33, v7
	v_lshlrev_b32_e32 v6, 12, v6
	v_mov_b32_e32 v7, v35
	v_or_b32_e32 v8, s6, v41
	v_lshl_add_u64 v[6:7], s[18:19], 0, v[6:7]
	s_and_b32 s16, s6, 0x1f80
	v_lshrrev_b32_e32 v8, 1, v8
	v_and_b32_e32 v8, 48, v8
	v_mov_b32_e32 v9, v35
	v_lshl_add_u64 v[6:7], v[6:7], 0, s[16:17]
	v_lshl_add_u64 v[6:7], v[6:7], 0, v[8:9]
	v_add_u32_e32 v34, -2, v34
	global_store_dwordx4 v[6:7], v[2:5], off
	global_store_dwordx4 v[6:7], v[32:35], off offset:64
	s_waitcnt lgkmcnt(0)

.LBB0_28:
	s_lshl_b32 s36, s16, 1
	s_lshl_b32 s37, s26, 1
	v_or_b32_e32 v34, s37, v4
	s_add_i32 s44, s36, 4
	s_add_i32 s45, s37, 4
	v_mov_b32_e32 v9, v35
	s_add_i32 s49, s37, 8
	v_lshlrev_b64 v[22:23], 14, v[34:35]
	v_or_b32_e32 v8, s44, v5
	v_or_b32_e32 v34, s45, v4
	v_mov_b32_e32 v7, v35
	v_or_b32_e32 v6, s36, v5
	s_add_i32 s51, s37, 12
	v_lshlrev_b64 v[8:9], 14, v[8:9]
	v_lshlrev_b64 v[24:25], 14, v[34:35]
	v_or_b32_e32 v34, s49, v4
	s_add_i32 s47, s36, 8
	s_add_i32 s50, s36, 12
	s_add_i32 s53, s37, 16
	v_lshlrev_b64 v[6:7], 14, v[6:7]
	v_lshl_add_u64 v[22:23], v[2:3], 0, v[22:23]
	v_lshl_add_u64 v[8:9], v[2:3], 0, v[8:9]
	v_lshlrev_b64 v[26:27], 14, v[34:35]
	v_or_b32_e32 v34, s51, v4
	v_mov_b32_e32 v11, v35
	v_mov_b32_e32 v13, v35
	s_add_i32 s55, s37, 20
	v_or_b32_e32 v10, s47, v5
	v_or_b32_e32 v12, s50, v5
	v_lshl_add_u64 v[6:7], v[2:3], 0, v[6:7]
	v_lshl_add_u64 v[24:25], v[2:3], 0, v[24:25]
	global_load_dword v61, v[22:23], off nt
	global_load_dword v79, v[6:7], off nt
	global_load_dword v84, v[24:25], off nt
	global_load_dword v85, v[8:9], off nt
	v_lshlrev_b64 v[8:9], 14, v[34:35]
	v_or_b32_e32 v34, s53, v4
	s_add_i32 s52, s36, 16
	s_add_i32 s54, s36, 20
	s_add_i32 s57, s37, 24
	v_lshlrev_b64 v[10:11], 14, v[10:11]
	v_lshlrev_b64 v[12:13], 14, v[12:13]
	v_lshl_add_u64 v[6:7], v[2:3], 0, v[26:27]
	v_lshl_add_u64 v[8:9], v[2:3], 0, v[8:9]
	v_lshlrev_b64 v[22:23], 14, v[34:35]
	v_or_b32_e32 v34, s55, v4
	v_mov_b32_e32 v15, v35
	v_mov_b32_e32 v17, v35
	s_add_i32 s56, s36, 24
	s_add_i32 s58, s36, 28
	s_add_i32 s59, s37, 28
	v_or_b32_e32 v14, s52, v5
	v_or_b32_e32 v16, s54, v5
	v_lshl_add_u64 v[10:11], v[2:3], 0, v[10:11]
	v_lshl_add_u64 v[12:13], v[2:3], 0, v[12:13]
	global_load_dword v86, v[6:7], off nt
	global_load_dword v87, v[10:11], off nt
	global_load_dword v88, v[8:9], off nt
	global_load_dword v89, v[12:13], off nt
	v_lshlrev_b64 v[8:9], 14, v[34:35]
	v_or_b32_e32 v34, s57, v4
	v_mov_b32_e32 v19, v35
	v_mov_b32_e32 v21, v35
	v_or_b32_e32 v18, s56, v5
	v_or_b32_e32 v20, s58, v5
	v_lshlrev_b64 v[14:15], 14, v[14:15]
	v_lshlrev_b64 v[16:17], 14, v[16:17]
	v_lshl_add_u64 v[6:7], v[2:3], 0, v[22:23]
	v_lshl_add_u64 v[8:9], v[2:3], 0, v[8:9]
	v_lshlrev_b64 v[10:11], 14, v[34:35]
	v_or_b32_e32 v34, s59, v4
	v_lshlrev_b64 v[18:19], 14, v[18:19]
	v_lshlrev_b64 v[20:21], 14, v[20:21]
	v_lshl_add_u64 v[14:15], v[2:3], 0, v[14:15]
	v_lshl_add_u64 v[16:17], v[2:3], 0, v[16:17]
	global_load_dword v90, v[6:7], off nt
	global_load_dword v91, v[14:15], off nt
	global_load_dword v92, v[8:9], off nt
	global_load_dword v93, v[16:17], off nt
	v_lshl_add_u64 v[6:7], v[2:3], 0, v[10:11]
	v_lshlrev_b64 v[8:9], 14, v[34:35]
	v_lshl_add_u64 v[18:19], v[2:3], 0, v[18:19]
	v_lshl_add_u64 v[20:21], v[2:3], 0, v[20:21]
	v_lshl_add_u64 v[8:9], v[2:3], 0, v[8:9]
	global_load_dword v34, v[6:7], off nt
	global_load_dword v94, v[18:19], off nt
	global_load_dword v95, v[8:9], off nt
	global_load_dword v96, v[20:21], off nt
	v_or_b32_e32 v8, s36, v1
	v_or_b32_e32 v6, s37, v38
	s_add_i32 s26, s26, 16
	s_add_i32 s16, s16, 16
	s_add_i32 s27, s27, -16
	v_mad_u64_u32 v[6:7], s[36:37], v6, s21, v[44:45]
	v_mad_u64_u32 v[8:9], s[36:37], v8, s21, v[44:45]
	v_or_b32_e32 v7, s44, v1
	v_or_b32_e32 v9, s45, v38
	v_or_b32_e32 v16, s47, v1
	v_or_b32_e32 v14, s49, v38
	v_or_b32_e32 v20, s50, v1
	v_or_b32_e32 v18, s51, v38
	v_or_b32_e32 v24, s52, v1
	v_or_b32_e32 v22, s53, v38
	v_or_b32_e32 v28, s54, v1
	v_or_b32_e32 v26, s55, v38
	v_or_b32_e32 v32, s56, v1
	v_or_b32_e32 v30, s57, v38
	v_or_b32_e32 v82, s58, v1
	v_or_b32_e32 v80, s59, v38
	s_cmp_lg_u32 s27, 0
	v_mad_u64_u32 v[10:11], s[36:37], v9, s21, v[44:45]
	v_mad_u64_u32 v[12:13], s[36:37], v7, s21, v[44:45]
	v_mad_u64_u32 v[14:15], s[36:37], v14, s21, v[44:45]
	v_mad_u64_u32 v[16:17], s[36:37], v16, s21, v[44:45]
	v_mad_u64_u32 v[18:19], s[36:37], v18, s21, v[44:45]
	v_mad_u64_u32 v[20:21], s[36:37], v20, s21, v[44:45]
	v_mad_u64_u32 v[22:23], s[36:37], v22, s21, v[44:45]
	v_mad_u64_u32 v[24:25], s[36:37], v24, s21, v[44:45]
	v_mad_u64_u32 v[26:27], s[36:37], v26, s21, v[44:45]
	v_mad_u64_u32 v[28:29], s[36:37], v28, s21, v[44:45]
	v_mad_u64_u32 v[30:31], s[36:37], v30, s21, v[44:45]
	v_mad_u64_u32 v[32:33], s[36:37], v32, s21, v[44:45]
	v_mad_u64_u32 v[80:81], s[36:37], v80, s21, v[44:45]
	v_mad_u64_u32 v[82:83], s[36:37], v82, s21, v[44:45]
	s_waitcnt vmcnt(15)
	ds_write_b32 v6, v61
	s_waitcnt vmcnt(14)
	ds_write_b32 v8, v79
	s_waitcnt vmcnt(13)
	ds_write_b32 v10, v84
	s_waitcnt vmcnt(12)
	ds_write_b32 v12, v85
	s_waitcnt vmcnt(11)
	ds_write_b32 v14, v86
	s_waitcnt vmcnt(10)
	ds_write_b32 v16, v87
	s_waitcnt vmcnt(9)
	ds_write_b32 v18, v88
	s_waitcnt vmcnt(8)
	ds_write_b32 v20, v89
	s_waitcnt vmcnt(7)
	ds_write_b32 v22, v90
	s_waitcnt vmcnt(6)
	ds_write_b32 v24, v91
	s_waitcnt vmcnt(5)
	ds_write_b32 v26, v92
	s_waitcnt vmcnt(4)
	ds_write_b32 v28, v93
	s_waitcnt vmcnt(3)
	ds_write_b32 v30, v34
	s_waitcnt vmcnt(2)
	ds_write_b32 v32, v94
	s_waitcnt vmcnt(1)
	ds_write_b32 v80, v95
	s_waitcnt vmcnt(0)
	ds_write_b32 v82, v96
	s_cbranch_scc1 .LBB0_28
	s_waitcnt lgkmcnt(0)
	ds_read2_b32 v[2:3], v63 offset1:33
	v_add_u32_e32 v16, 0x800, v63
	v_add_u32_e32 v18, 0x400, v63
	v_add_u32_e32 v19, 0xc00, v63
	ds_read2_b32 v[4:5], v16 offset0:16 offset1:49
	ds_read2_b32 v[6:7], v63 offset0:66 offset1:99
	ds_read2_b32 v[8:9], v16 offset0:82 offset1:115
	ds_read2_b32 v[10:11], v63 offset0:132 offset1:165
	ds_read2_b32 v[12:13], v16 offset0:148 offset1:181
	ds_read2_b32 v[14:15], v63 offset0:198 offset1:231
	ds_read2_b32 v[16:17], v16 offset0:214 offset1:247
	ds_read2_b32 v[26:27], v18 offset0:8 offset1:41
	ds_read2_b32 v[28:29], v19 offset0:24 offset1:57
	ds_read2_b32 v[30:31], v18 offset0:74 offset1:107
	ds_read2_b32 v[32:33], v19 offset0:90 offset1:123
	ds_read2_b32 v[80:81], v18 offset0:140 offset1:173
	ds_read2_b32 v[82:83], v19 offset0:156 offset1:189
	ds_read2_b32 v[84:85], v18 offset0:206 offset1:239
	ds_read2_b32 v[86:87], v19 offset0:222 offset1:255
	s_waitcnt lgkmcnt(14)
	v_max_f32_e64 v18, |v4|, |v4|
	v_max_f32_e64 v19, |v2|, |v2|
	v_max_f32_e32 v18, v19, v18
	v_max_f32_e64 v19, |v5|, |v5|
	v_max_f32_e64 v20, |v3|, |v3|
	v_max_f32_e32 v19, v20, v19
	v_max3_f32 v18, v18, 0, v19
	s_waitcnt lgkmcnt(12)
	v_max_f32_e64 v19, |v8|, |v8|
	v_max_f32_e64 v20, |v6|, |v6|
	v_max_f32_e32 v19, v20, v19
	v_max_f32_e64 v20, |v9|, |v9|
	v_max_f32_e64 v21, |v7|, |v7|
	v_max_f32_e32 v20, v21, v20
	v_max3_f32 v18, v18, v19, v20
	s_waitcnt lgkmcnt(10)
	v_max_f32_e64 v19, |v12|, |v12|
	v_max_f32_e64 v20, |v10|, |v10|
	v_max_f32_e32 v19, v20, v19
	v_max_f32_e64 v20, |v13|, |v13|
	v_max_f32_e64 v21, |v11|, |v11|
	v_max_f32_e32 v20, v21, v20
	v_max3_f32 v18, v18, v19, v20
	s_waitcnt lgkmcnt(8)
	v_max_f32_e64 v19, |v16|, |v16|
	v_max_f32_e64 v20, |v14|, |v14|
	v_max_f32_e32 v19, v20, v19
	v_max_f32_e64 v20, |v17|, |v17|
	v_max_f32_e64 v21, |v15|, |v15|
	v_max_f32_e32 v20, v21, v20
	v_max3_f32 v18, v18, v19, v20
	s_waitcnt lgkmcnt(6)
	v_max_f32_e64 v19, |v28|, |v28|
	v_max_f32_e64 v20, |v26|, |v26|
	v_max_f32_e32 v19, v20, v19
	v_max_f32_e64 v20, |v29|, |v29|
	v_max_f32_e64 v21, |v27|, |v27|
	v_max_f32_e32 v20, v21, v20
	v_max3_f32 v18, v18, v19, v20
	s_waitcnt lgkmcnt(4)
	v_max_f32_e64 v19, |v32|, |v32|
	v_max_f32_e64 v20, |v30|, |v30|
	v_max_f32_e32 v19, v20, v19
	v_max_f32_e64 v20, |v33|, |v33|
	v_max_f32_e64 v21, |v31|, |v31|
	v_max_f32_e32 v20, v21, v20
	v_max3_f32 v18, v18, v19, v20
	s_waitcnt lgkmcnt(2)
	v_max_f32_e64 v19, |v82|, |v82|
	v_max_f32_e64 v20, |v80|, |v80|
	v_max_f32_e32 v19, v20, v19
	v_max_f32_e64 v20, |v83|, |v83|
	v_max_f32_e64 v21, |v81|, |v81|
	v_max_f32_e32 v20, v21, v20
	v_max3_f32 v18, v18, v19, v20
	s_waitcnt lgkmcnt(0)
	v_max_f32_e64 v19, |v86|, |v86|
	v_max_f32_e64 v20, |v84|, |v84|
	v_max_f32_e32 v19, v20, v19
	v_max_f32_e64 v20, |v87|, |v87|
	v_max_f32_e64 v21, |v85|, |v85|
	v_max_f32_e32 v20, v21, v20
	v_max3_f32 v18, v18, v19, v20
	v_bfe_u32 v18, v18, 23, 8
	v_max_u32_e32 v34, 3, v18
	v_lshlrev_b32_e32 v18, 23, v34
	v_sub_u32_e32 v61, 0x80000000, v18
	v_mul_f32_e32 v4, v4, v61
	v_med3_f32 v18, v4, s40, v78
	v_mul_f32_e32 v4, v5, v61
	v_mul_f32_e32 v5, v8, v61
	v_med3_f32 v19, v4, s40, v78
	v_mul_f32_e32 v4, v6, v61
	v_med3_f32 v20, v5, s40, v78
	v_mul_f32_e32 v5, v7, v61
	v_mul_f32_e32 v6, v9, v61
	v_mul_f32_e32 v7, v12, v61
	v_mul_f32_e32 v8, v13, v61
	v_mul_f32_e32 v9, v16, v61
	v_med3_f32 v21, v6, s40, v78
	v_mul_f32_e32 v6, v10, v61
	v_med3_f32 v22, v7, s40, v78
	v_mul_f32_e32 v7, v11, v61
	v_med3_f32 v23, v8, s40, v78
	v_mul_f32_e32 v8, v14, v61
	v_med3_f32 v24, v9, s40, v78
	v_mul_f32_e32 v9, v15, v61
	v_mul_f32_e32 v10, v17, v61
	v_mul_f32_e32 v11, v28, v61
	v_mul_f32_e32 v12, v29, v61
	v_mul_f32_e32 v13, v32, v61
	v_mul_f32_e32 v14, v33, v61
	v_mul_f32_e32 v15, v82, v61
	v_mul_f32_e32 v16, v83, v61
	v_mul_f32_e32 v17, v86, v61
	v_mul_f32_e32 v2, v2, v61
	v_mul_f32_e32 v3, v3, v61
	v_med3_f32 v25, v10, s40, v78
	v_mul_f32_e32 v10, v26, v61
	v_med3_f32 v26, v11, s40, v78
	v_mul_f32_e32 v11, v27, v61
	v_med3_f32 v27, v12, s40, v78
	v_mul_f32_e32 v12, v30, v61
	v_med3_f32 v28, v13, s40, v78
	v_mul_f32_e32 v13, v31, v61
	v_med3_f32 v29, v14, s40, v78
	v_mul_f32_e32 v14, v80, v61
	v_med3_f32 v30, v15, s40, v78
	v_mul_f32_e32 v15, v81, v61
	v_med3_f32 v31, v16, s40, v78
	v_mul_f32_e32 v16, v84, v61
	v_med3_f32 v32, v17, s40, v78
	v_mul_f32_e32 v17, v85, v61
	v_mul_f32_e32 v33, v87, v61
	v_med3_f32 v2, v2, s40, v78
	v_med3_f32 v3, v3, s40, v78
	v_med3_f32 v4, v4, s40, v78
	v_med3_f32 v5, v5, s40, v78
	v_med3_f32 v6, v6, s40, v78
	v_med3_f32 v7, v7, s40, v78
	v_med3_f32 v8, v8, s40, v78
	v_med3_f32 v9, v9, s40, v78
	v_med3_f32 v10, v10, s40, v78
	v_med3_f32 v11, v11, s40, v78
	v_med3_f32 v12, v12, s40, v78
	v_med3_f32 v13, v13, s40, v78
	v_med3_f32 v14, v14, s40, v78
	v_med3_f32 v15, v15, s40, v78
	v_med3_f32 v16, v16, s40, v78
	v_med3_f32 v17, v17, s40, v78
	v_med3_f32 v33, v33, s40, v78
	s_and_b32 s11, 0xffff, s11
	v_cvt_scalef32_2xpk16_fp6_f32 v[2:7], v[2:17], v[18:33], 1.0
	v_mov_b32_e32 v32, v6
	v_or_b32_e32 v6, s11, v40
	v_mov_b32_e32 v33, v7
	v_mul_u32_u24_e32 v6, 0x1800, v6
	v_mov_b32_e32 v7, v35
	v_or_b32_e32 v8, s9, v41
	v_lshl_add_u64 v[6:7], s[14:15], 0, v[6:7]
	s_and_b32 s16, s8, 0x7f80
	v_lshrrev_b32_e32 v8, 1, v8
	v_and_b32_e32 v8, 48, v8
	v_mov_b32_e32 v9, v35
	v_lshl_add_u64 v[6:7], v[6:7], 0, s[16:17]
	v_lshl_add_u64 v[6:7], v[6:7], 0, v[8:9]
	v_lshl_add_u64 v[8:9], v[6:7], 0, s[22:23]
	v_add_co_u32_e32 v6, vcc, 0x800000, v6
	v_add_u32_e32 v34, -2, v34
	s_nop 0
	v_addc_co_u32_e32 v7, vcc, 0, v7, vcc
	global_store_dwordx4 v[6:7], v[2:5], off offset:2048
	global_store_dwordx4 v[8:9], v[32:35], off offset:64
	s_waitcnt lgkmcnt(0)
	s_mov_b64 s[8:9], 0

.LBB0_32:
	s_lshl_b32 s10, s11, 1
	s_lshl_b32 s16, s6, 1
	v_or_b32_e32 v34, s16, v4
	s_add_i32 s36, s10, 4
	s_add_i32 s37, s16, 4
	v_mov_b32_e32 v9, v35
	s_add_i32 s45, s16, 8
	v_lshlrev_b64 v[22:23], 14, v[34:35]
	v_or_b32_e32 v8, s36, v5
	v_or_b32_e32 v34, s37, v4
	v_mov_b32_e32 v7, v35
	v_or_b32_e32 v6, s10, v5
	s_add_i32 s49, s16, 12
	v_lshlrev_b64 v[8:9], 14, v[8:9]
	v_lshlrev_b64 v[24:25], 14, v[34:35]
	v_or_b32_e32 v34, s45, v4
	s_add_i32 s44, s10, 8
	s_add_i32 s47, s10, 12
	s_add_i32 s51, s16, 16
	v_lshlrev_b64 v[6:7], 14, v[6:7]
	v_lshl_add_u64 v[22:23], v[2:3], 0, v[22:23]
	v_lshl_add_u64 v[8:9], v[2:3], 0, v[8:9]
	v_lshlrev_b64 v[26:27], 14, v[34:35]
	v_or_b32_e32 v34, s49, v4
	v_mov_b32_e32 v11, v35
	v_mov_b32_e32 v13, v35
	s_add_i32 s53, s16, 20
	v_or_b32_e32 v10, s44, v5
	v_or_b32_e32 v12, s47, v5
	v_lshl_add_u64 v[6:7], v[2:3], 0, v[6:7]
	v_lshl_add_u64 v[24:25], v[2:3], 0, v[24:25]
	global_load_dword v61, v[22:23], off nt
	global_load_dword v79, v[6:7], off nt
	global_load_dword v84, v[24:25], off nt
	global_load_dword v85, v[8:9], off nt
	v_lshlrev_b64 v[8:9], 14, v[34:35]
	v_or_b32_e32 v34, s51, v4
	s_add_i32 s50, s10, 16
	s_add_i32 s52, s10, 20
	s_add_i32 s55, s16, 24
	v_lshlrev_b64 v[10:11], 14, v[10:11]
	v_lshlrev_b64 v[12:13], 14, v[12:13]
	v_lshl_add_u64 v[6:7], v[2:3], 0, v[26:27]
	v_lshl_add_u64 v[8:9], v[2:3], 0, v[8:9]
	v_lshlrev_b64 v[22:23], 14, v[34:35]
	v_or_b32_e32 v34, s53, v4
	v_mov_b32_e32 v15, v35
	v_mov_b32_e32 v17, v35
	s_add_i32 s54, s10, 24
	s_add_i32 s56, s10, 28
	s_add_i32 s57, s16, 28
	v_or_b32_e32 v14, s50, v5
	v_or_b32_e32 v16, s52, v5
	v_lshl_add_u64 v[10:11], v[2:3], 0, v[10:11]
	v_lshl_add_u64 v[12:13], v[2:3], 0, v[12:13]
	global_load_dword v86, v[6:7], off nt
	global_load_dword v87, v[10:11], off nt
	global_load_dword v88, v[8:9], off nt
	global_load_dword v89, v[12:13], off nt
	v_lshlrev_b64 v[8:9], 14, v[34:35]
	v_or_b32_e32 v34, s55, v4
	v_mov_b32_e32 v19, v35
	v_mov_b32_e32 v21, v35
	v_or_b32_e32 v18, s54, v5
	v_or_b32_e32 v20, s56, v5
	v_lshlrev_b64 v[14:15], 14, v[14:15]
	v_lshlrev_b64 v[16:17], 14, v[16:17]
	v_lshl_add_u64 v[6:7], v[2:3], 0, v[22:23]
	v_lshl_add_u64 v[8:9], v[2:3], 0, v[8:9]
	v_lshlrev_b64 v[10:11], 14, v[34:35]
	v_or_b32_e32 v34, s57, v4
	v_lshlrev_b64 v[18:19], 14, v[18:19]
	v_lshlrev_b64 v[20:21], 14, v[20:21]
	v_lshl_add_u64 v[14:15], v[2:3], 0, v[14:15]
	v_lshl_add_u64 v[16:17], v[2:3], 0, v[16:17]
	global_load_dword v90, v[6:7], off nt
	global_load_dword v91, v[14:15], off nt
	global_load_dword v92, v[8:9], off nt
	global_load_dword v93, v[16:17], off nt
	v_lshl_add_u64 v[6:7], v[2:3], 0, v[10:11]
	v_lshlrev_b64 v[8:9], 14, v[34:35]
	v_lshl_add_u64 v[18:19], v[2:3], 0, v[18:19]
	v_lshl_add_u64 v[20:21], v[2:3], 0, v[20:21]
	v_lshl_add_u64 v[8:9], v[2:3], 0, v[8:9]
	global_load_dword v34, v[6:7], off nt
	global_load_dword v94, v[18:19], off nt
	global_load_dword v95, v[8:9], off nt
	global_load_dword v96, v[20:21], off nt
	v_or_b32_e32 v8, s10, v1
	v_or_b32_e32 v6, s16, v38
	s_add_i32 s6, s6, 16
	s_add_i32 s11, s11, 16
	s_add_i32 s7, s7, -16
	v_mad_u64_u32 v[6:7], s[26:27], v6, s21, v[44:45]
	v_mad_u64_u32 v[8:9], s[26:27], v8, s21, v[44:45]
	v_or_b32_e32 v7, s36, v1
	v_or_b32_e32 v9, s37, v38
	v_or_b32_e32 v16, s44, v1
	v_or_b32_e32 v14, s45, v38
	v_or_b32_e32 v20, s47, v1
	v_or_b32_e32 v18, s49, v38
	v_or_b32_e32 v24, s50, v1
	v_or_b32_e32 v22, s51, v38
	v_or_b32_e32 v28, s52, v1
	v_or_b32_e32 v26, s53, v38
	v_or_b32_e32 v32, s54, v1
	v_or_b32_e32 v30, s55, v38
	v_or_b32_e32 v82, s56, v1
	v_or_b32_e32 v80, s57, v38
	s_cmp_lg_u32 s7, 0
	v_mad_u64_u32 v[10:11], s[26:27], v9, s21, v[44:45]
	v_mad_u64_u32 v[12:13], s[26:27], v7, s21, v[44:45]
	v_mad_u64_u32 v[14:15], s[26:27], v14, s21, v[44:45]
	v_mad_u64_u32 v[16:17], s[26:27], v16, s21, v[44:45]
	v_mad_u64_u32 v[18:19], s[26:27], v18, s21, v[44:45]
	v_mad_u64_u32 v[20:21], s[26:27], v20, s21, v[44:45]
	v_mad_u64_u32 v[22:23], s[26:27], v22, s21, v[44:45]
	v_mad_u64_u32 v[24:25], s[26:27], v24, s21, v[44:45]
	v_mad_u64_u32 v[26:27], s[26:27], v26, s21, v[44:45]
	v_mad_u64_u32 v[28:29], s[26:27], v28, s21, v[44:45]
	v_mad_u64_u32 v[30:31], s[26:27], v30, s21, v[44:45]
	v_mad_u64_u32 v[32:33], s[26:27], v32, s21, v[44:45]
	v_mad_u64_u32 v[80:81], s[26:27], v80, s21, v[44:45]
	v_mad_u64_u32 v[82:83], s[26:27], v82, s21, v[44:45]
	s_waitcnt vmcnt(15)
	ds_write_b32 v6, v61
	s_waitcnt vmcnt(14)
	ds_write_b32 v8, v79
	s_waitcnt vmcnt(13)
	ds_write_b32 v10, v84
	s_waitcnt vmcnt(12)
	ds_write_b32 v12, v85
	s_waitcnt vmcnt(11)
	ds_write_b32 v14, v86
	s_waitcnt vmcnt(10)
	ds_write_b32 v16, v87
	s_waitcnt vmcnt(9)
	ds_write_b32 v18, v88
	s_waitcnt vmcnt(8)
	ds_write_b32 v20, v89
	s_waitcnt vmcnt(7)
	ds_write_b32 v22, v90
	s_waitcnt vmcnt(6)
	ds_write_b32 v24, v91
	s_waitcnt vmcnt(5)
	ds_write_b32 v26, v92
	s_waitcnt vmcnt(4)
	ds_write_b32 v28, v93
	s_waitcnt vmcnt(3)
	ds_write_b32 v30, v34
	s_waitcnt vmcnt(2)
	ds_write_b32 v32, v94
	s_waitcnt vmcnt(1)
	ds_write_b32 v80, v95
	s_waitcnt vmcnt(0)
	ds_write_b32 v82, v96
	s_cbranch_scc1 .LBB0_32
	s_waitcnt lgkmcnt(0)
	ds_read2_b32 v[6:7], v65 offset1:8
	ds_read2_b32 v[10:11], v65 offset0:33 offset1:41
	ds_read2_b32 v[12:13], v65 offset0:66 offset1:74
	ds_read2_b32 v[14:15], v65 offset0:99 offset1:107
	ds_read2_b32 v[16:17], v65 offset0:132 offset1:140
	ds_read2_b32 v[18:19], v65 offset0:165 offset1:173
	s_waitcnt lgkmcnt(5)
	v_bfe_u32 v2, v6, 16, 1
	v_add3_u32 v2, v6, v2, s41
	s_waitcnt lgkmcnt(4)
	v_bfe_u32 v3, v10, 16, 1
	v_lshrrev_b32_e32 v2, 16, v2
	v_add3_u32 v3, v10, v3, s41
	v_and_or_b32 v2, v3, s42, v2
	s_waitcnt lgkmcnt(3)
	v_bfe_u32 v3, v12, 16, 1
	v_add3_u32 v3, v12, v3, s41
	s_waitcnt lgkmcnt(2)
	v_bfe_u32 v4, v14, 16, 1
	ds_read2_b32 v[20:21], v65 offset0:198 offset1:206
	v_lshrrev_b32_e32 v3, 16, v3
	v_add3_u32 v4, v14, v4, s41
	ds_read2_b32 v[22:23], v65 offset0:231 offset1:239
	v_and_or_b32 v3, v4, s42, v3
	s_waitcnt lgkmcnt(3)
	v_bfe_u32 v4, v16, 16, 1
	v_add3_u32 v4, v16, v4, s41
	s_waitcnt lgkmcnt(2)
	v_bfe_u32 v5, v18, 16, 1
	v_lshrrev_b32_e32 v4, 16, v4
	v_add3_u32 v5, v18, v5, s41
	v_and_or_b32 v4, v5, s42, v4
	s_waitcnt lgkmcnt(1)
	v_bfe_u32 v5, v20, 16, 1
	v_add3_u32 v5, v20, v5, s41
	s_waitcnt lgkmcnt(0)
	v_bfe_u32 v6, v22, 16, 1
	v_lshrrev_b32_e32 v5, 16, v5
	v_add3_u32 v6, v22, v6, s41
	v_and_or_b32 v5, v6, s42, v5
	v_or_b32_e32 v6, s8, v64
	s_lshl_b32 s16, s9, 1
	v_mul_u32_u24_e32 v6, 0xc00, v6
	v_lshl_add_u64 v[8:9], v[48:49], 0, s[16:17]
	v_lshlrev_b32_e32 v34, 1, v6
	v_lshl_add_u64 v[24:25], v[8:9], 0, v[34:35]
	global_store_dwordx4 v[24:25], v[2:5], off
	v_bfe_u32 v6, v23, 16, 1
	v_add3_u32 v6, v23, v6, s41
	v_bfe_u32 v2, v7, 16, 1
	v_add3_u32 v2, v7, v2, s41
	v_bfe_u32 v3, v11, 16, 1
	v_lshrrev_b32_e32 v2, 16, v2
	v_add3_u32 v3, v11, v3, s41
	v_and_or_b32 v2, v3, s42, v2
	v_bfe_u32 v3, v13, 16, 1
	v_add3_u32 v3, v13, v3, s41
	v_bfe_u32 v4, v15, 16, 1
	v_lshrrev_b32_e32 v3, 16, v3
	v_add3_u32 v4, v15, v4, s41
	v_and_or_b32 v3, v4, s42, v3
	v_bfe_u32 v4, v17, 16, 1
	v_add3_u32 v4, v17, v4, s41
	v_bfe_u32 v5, v19, 16, 1
	v_lshrrev_b32_e32 v4, 16, v4
	v_add3_u32 v5, v19, v5, s41
	v_and_or_b32 v4, v5, s42, v4
	v_bfe_u32 v5, v21, 16, 1
	v_add3_u32 v5, v21, v5, s41
	v_lshrrev_b32_e32 v5, 16, v5
	v_and_or_b32 v5, v6, s42, v5
	v_or_b32_e32 v6, s8, v66
	v_mul_u32_u24_e32 v10, 0xc00, v6
	v_lshlrev_b32_e32 v34, 1, v10
	ds_read2_b32 v[6:7], v65 offset0:16 offset1:24
	v_lshl_add_u64 v[10:11], v[8:9], 0, v[34:35]
	global_store_dwordx4 v[10:11], v[2:5], off
	ds_read2_b32 v[10:11], v65 offset0:49 offset1:57
	ds_read2_b32 v[12:13], v65 offset0:82 offset1:90
	ds_read2_b32 v[14:15], v65 offset0:115 offset1:123
	s_waitcnt lgkmcnt(3)
	v_bfe_u32 v2, v6, 16, 1
	v_add3_u32 v2, v6, v2, s41
	s_waitcnt lgkmcnt(2)
	v_bfe_u32 v3, v10, 16, 1
	ds_read2_b32 v[16:17], v65 offset0:148 offset1:156
	v_lshrrev_b32_e32 v2, 16, v2
	v_add3_u32 v3, v10, v3, s41
	ds_read2_b32 v[18:19], v65 offset0:181 offset1:189
	v_and_or_b32 v2, v3, s42, v2
	s_waitcnt lgkmcnt(3)
	v_bfe_u32 v3, v12, 16, 1
	v_add3_u32 v3, v12, v3, s41
	s_waitcnt lgkmcnt(2)
	v_bfe_u32 v4, v14, 16, 1
	ds_read2_b32 v[20:21], v65 offset0:214 offset1:222
	v_lshrrev_b32_e32 v3, 16, v3
	v_add3_u32 v4, v14, v4, s41
	ds_read2_b32 v[22:23], v65 offset0:247 offset1:255
	v_and_or_b32 v3, v4, s42, v3
	s_waitcnt lgkmcnt(3)
	v_bfe_u32 v4, v16, 16, 1
	v_add3_u32 v4, v16, v4, s41
	s_waitcnt lgkmcnt(2)
	v_bfe_u32 v5, v18, 16, 1
	v_lshrrev_b32_e32 v4, 16, v4
	v_add3_u32 v5, v18, v5, s41
	v_and_or_b32 v4, v5, s42, v4
	s_waitcnt lgkmcnt(1)
	v_bfe_u32 v5, v20, 16, 1
	v_add3_u32 v5, v20, v5, s41
	s_waitcnt lgkmcnt(0)
	v_bfe_u32 v6, v22, 16, 1
	v_lshrrev_b32_e32 v5, 16, v5
	v_add3_u32 v6, v22, v6, s41
	v_and_or_b32 v5, v6, s42, v5
	v_or_b32_e32 v6, s8, v67
	v_mul_u32_u24_e32 v6, 0xc00, v6
	v_lshlrev_b32_e32 v34, 1, v6
	v_lshl_add_u64 v[24:25], v[8:9], 0, v[34:35]
	global_store_dwordx4 v[24:25], v[2:5], off
	v_bfe_u32 v6, v23, 16, 1
	v_add3_u32 v6, v23, v6, s41
	v_bfe_u32 v2, v7, 16, 1
	v_add3_u32 v2, v7, v2, s41
	v_bfe_u32 v3, v11, 16, 1
	v_lshrrev_b32_e32 v2, 16, v2
	v_add3_u32 v3, v11, v3, s41
	v_and_or_b32 v2, v3, s42, v2
	v_bfe_u32 v3, v13, 16, 1
	v_add3_u32 v3, v13, v3, s41
	v_bfe_u32 v4, v15, 16, 1
	v_lshrrev_b32_e32 v3, 16, v3
	v_add3_u32 v4, v15, v4, s41
	v_and_or_b32 v3, v4, s42, v3
	v_bfe_u32 v4, v17, 16, 1
	v_add3_u32 v4, v17, v4, s41
	v_bfe_u32 v5, v19, 16, 1
	v_lshrrev_b32_e32 v4, 16, v4
	v_add3_u32 v5, v19, v5, s41
	v_and_or_b32 v4, v5, s42, v4
	v_bfe_u32 v5, v21, 16, 1
	v_add3_u32 v5, v21, v5, s41
	v_lshrrev_b32_e32 v5, 16, v5
	v_and_or_b32 v5, v6, s42, v5
	v_or_b32_e32 v6, s8, v68
	v_mul_u32_u24_e32 v6, 0xc00, v6
	v_lshlrev_b32_e32 v34, 1, v6
	v_lshl_add_u64 v[6:7], v[8:9], 0, v[34:35]
	global_store_dwordx4 v[6:7], v[2:5], off
	s_waitcnt lgkmcnt(0)

.Lp0_kvb_fast:
	v_lshl_add_u64 v[24:25], v[18:19], 0, s[26:27]
	global_load_dword v100, v[24:25], off nt
	v_lshl_add_u64 v[24:25], v[16:17], 0, s[26:27]
	global_load_dword v101, v[24:25], off nt
	v_lshl_add_u64 v[24:25], v[14:15], 0, s[26:27]
	global_load_dword v102, v[24:25], off nt
	v_lshl_add_u64 v[24:25], v[12:13], 0, s[26:27]
	global_load_dword v103, v[24:25], off nt
	v_lshl_add_u64 v[24:25], v[10:11], 0, s[26:27]
	global_load_dword v104, v[24:25], off nt
	v_lshl_add_u64 v[24:25], v[8:9], 0, s[26:27]
	global_load_dword v105, v[24:25], off nt
	v_lshl_add_u64 v[24:25], v[6:7], 0, s[26:27]
	global_load_dword v106, v[24:25], off nt
	v_lshl_add_u64 v[24:25], v[4:5], 0, s[26:27]
	global_load_dword v107, v[24:25], off nt
	v_lshl_add_u64 v[24:25], s[8:9], 0, v[34:35]
	global_load_dword v108, v[24:25], off nt
	v_lshl_add_u64 v[20:21], s[8:9], 0, v[2:3]
	global_load_dword v109, v[20:21], off offset:8
	global_load_dword v110, v[20:21], off offset:16
	global_load_dword v111, v[20:21], off offset:24
	global_load_dword v112, v[20:21], off offset:32
	global_load_dword v113, v[20:21], off offset:40
	global_load_dword v114, v[20:21], off offset:48
	global_load_dword v115, v[20:21], off offset:56
	s_waitcnt vmcnt(0)
	v_mul_f32_e32 v100, 0x41800000, v100
	v_mul_f32_e32 v100, v100, v108
	ds_write_b32 v22, v100
	v_mul_f32_e32 v101, 0x41800000, v101
	v_mul_f32_e32 v101, v101, v109
	ds_write_b32 v22, v101 offset:264
	v_mul_f32_e32 v102, 0x41800000, v102
	v_mul_f32_e32 v102, v102, v110
	ds_write_b32 v22, v102 offset:528
	v_mul_f32_e32 v103, 0x41800000, v103
	v_mul_f32_e32 v103, v103, v111
	ds_write_b32 v22, v103 offset:792
	v_mul_f32_e32 v104, 0x41800000, v104
	v_mul_f32_e32 v104, v104, v112
	ds_write_b32 v22, v104 offset:1056
	v_mul_f32_e32 v105, 0x41800000, v105
	v_mul_f32_e32 v105, v105, v113
	ds_write_b32 v22, v105 offset:1320
	v_mul_f32_e32 v106, 0x41800000, v106
	v_mul_f32_e32 v106, v106, v114
	ds_write_b32 v22, v106 offset:1584
	v_mul_f32_e32 v107, 0x41800000, v107
	v_mul_f32_e32 v107, v107, v115
	ds_write_b32 v22, v107 offset:1848
	s_add_u32 s26, s26, 0x40000
	s_addc_u32 s27, s27, 0
	s_add_u32 s8, s8, 64
	s_addc_u32 s9, s9, 0
	s_cmp_lg_u32 s26, 0x100000
	v_add_u32_e32 v22, 0x840, v22
	s_cbranch_scc1 .Lp0_kvb_fast
	s_branch .LBB0_54
.Lp0_kvb_slow:
	v_lshl_add_u64 v[20:21], v[18:19], 0, s[26:27]
	global_load_dword v20, v[20:21], off nt
	v_cndmask_b32_e64 v21, 0, 1, s[36:37]
	v_cmp_ne_u32_e64 s[6:7], 1, v21
	s_andn2_b64 vcc, exec, s[36:37]
	s_waitcnt vmcnt(0)
	v_mul_f32_e32 v20, 0x41800000, v20
	s_cbranch_vccnz .LBB0_40
	v_lshl_add_u64 v[24:25], s[8:9], 0, v[34:35]
	global_load_dword v21, v[24:25], off nt
	s_waitcnt vmcnt(0)
	v_mul_f32_e32 v20, v20, v21
.LBB0_40:
	v_lshl_add_u64 v[24:25], v[16:17], 0, s[26:27]
	global_load_dword v21, v[24:25], off nt
	ds_write_b32 v22, v20
	s_and_b64 vcc, exec, s[6:7]
	s_waitcnt vmcnt(0)
	v_mul_f32_e32 v23, 0x41800000, v21
	v_lshl_add_u64 v[20:21], s[8:9], 0, v[2:3]
	s_cbranch_vccnz .LBB0_42
	global_load_dword v24, v[20:21], off offset:8
	s_waitcnt vmcnt(0)
	v_mul_f32_e32 v23, v23, v24
.LBB0_42:
	v_lshl_add_u64 v[24:25], v[14:15], 0, s[26:27]
	global_load_dword v24, v[24:25], off nt
	ds_write_b32 v22, v23 offset:264
	s_and_b64 vcc, exec, s[6:7]
	s_waitcnt vmcnt(0)
	v_mul_f32_e32 v23, 0x41800000, v24
	s_cbranch_vccnz .LBB0_44
	global_load_dword v24, v[20:21], off offset:16
	s_waitcnt vmcnt(0)
	v_mul_f32_e32 v23, v23, v24
.LBB0_44:
	v_lshl_add_u64 v[24:25], v[12:13], 0, s[26:27]
	global_load_dword v24, v[24:25], off nt
	ds_write_b32 v22, v23 offset:528
	s_and_b64 vcc, exec, s[6:7]
	s_waitcnt vmcnt(0)
	v_mul_f32_e32 v23, 0x41800000, v24
	s_cbranch_vccnz .LBB0_46
	global_load_dword v24, v[20:21], off offset:24
	s_waitcnt vmcnt(0)
	v_mul_f32_e32 v23, v23, v24
.LBB0_46:
	v_lshl_add_u64 v[24:25], v[10:11], 0, s[26:27]
	global_load_dword v24, v[24:25], off nt
	ds_write_b32 v22, v23 offset:792
	s_and_b64 vcc, exec, s[6:7]
	s_waitcnt vmcnt(0)
	v_mul_f32_e32 v23, 0x41800000, v24
	s_cbranch_vccnz .LBB0_48
	global_load_dword v24, v[20:21], off offset:32
	s_waitcnt vmcnt(0)
	v_mul_f32_e32 v23, v23, v24
.LBB0_48:
	v_lshl_add_u64 v[24:25], v[8:9], 0, s[26:27]
	global_load_dword v24, v[24:25], off nt
	ds_write_b32 v22, v23 offset:1056
	s_and_b64 vcc, exec, s[6:7]
	s_waitcnt vmcnt(0)
	v_mul_f32_e32 v23, 0x41800000, v24
	s_cbranch_vccnz .LBB0_50
	global_load_dword v24, v[20:21], off offset:40
	s_waitcnt vmcnt(0)
	v_mul_f32_e32 v23, v23, v24
.LBB0_50:
	v_lshl_add_u64 v[24:25], v[6:7], 0, s[26:27]
	global_load_dword v24, v[24:25], off nt
	ds_write_b32 v22, v23 offset:1320
	s_and_b64 vcc, exec, s[6:7]
	s_waitcnt vmcnt(0)
	v_mul_f32_e32 v23, 0x41800000, v24
	s_cbranch_vccnz .LBB0_52
	global_load_dword v24, v[20:21], off offset:48
	s_waitcnt vmcnt(0)
	v_mul_f32_e32 v23, v23, v24
.LBB0_52:
	v_lshl_add_u64 v[24:25], v[4:5], 0, s[26:27]
	global_load_dword v24, v[24:25], off nt
	ds_write_b32 v22, v23 offset:1584
	s_and_b64 vcc, exec, s[6:7]
	s_waitcnt vmcnt(0)
	v_mul_f32_e32 v23, 0x41800000, v24
	s_cbranch_vccnz .LBB0_37
	global_load_dword v20, v[20:21], off offset:56
	s_waitcnt vmcnt(0)
	v_mul_f32_e32 v23, v23, v20
	s_branch .LBB0_37

.Lp0_qb_fast:
	v_lshl_add_u64 v[24:25], v[18:19], 0, s[26:27]
	global_load_dword v100, v[24:25], off nt
	v_lshl_add_u64 v[24:25], v[16:17], 0, s[26:27]
	global_load_dword v101, v[24:25], off nt
	v_lshl_add_u64 v[24:25], v[14:15], 0, s[26:27]
	global_load_dword v102, v[24:25], off nt
	v_lshl_add_u64 v[24:25], v[12:13], 0, s[26:27]
	global_load_dword v103, v[24:25], off nt
	v_lshl_add_u64 v[24:25], v[10:11], 0, s[26:27]
	global_load_dword v104, v[24:25], off nt
	v_lshl_add_u64 v[24:25], v[8:9], 0, s[26:27]
	global_load_dword v105, v[24:25], off nt
	v_lshl_add_u64 v[24:25], v[6:7], 0, s[26:27]
	global_load_dword v106, v[24:25], off nt
	v_lshl_add_u64 v[24:25], v[2:3], 0, s[26:27]
	global_load_dword v107, v[24:25], off nt
	v_lshl_add_u64 v[24:25], s[8:9], 0, v[34:35]
	global_load_dword v108, v[24:25], off nt
	v_lshl_add_u64 v[20:21], s[8:9], 0, v[4:5]
	global_load_dword v109, v[20:21], off offset:8
	global_load_dword v110, v[20:21], off offset:16
	global_load_dword v111, v[20:21], off offset:24
	global_load_dword v112, v[20:21], off offset:32
	global_load_dword v113, v[20:21], off offset:40
	global_load_dword v114, v[20:21], off offset:48
	global_load_dword v115, v[20:21], off offset:56
	s_waitcnt vmcnt(0)
	v_mul_f32_e32 v100, 0x42000000, v100
	v_mul_f32_e32 v100, v100, v108
	ds_write_b32 v22, v100
	v_mul_f32_e32 v101, 0x42000000, v101
	v_mul_f32_e32 v101, v101, v109
	ds_write_b32 v22, v101 offset:264
	v_mul_f32_e32 v102, 0x42000000, v102
	v_mul_f32_e32 v102, v102, v110
	ds_write_b32 v22, v102 offset:528
	v_mul_f32_e32 v103, 0x42000000, v103
	v_mul_f32_e32 v103, v103, v111
	ds_write_b32 v22, v103 offset:792
	v_mul_f32_e32 v104, 0x42000000, v104
	v_mul_f32_e32 v104, v104, v112
	ds_write_b32 v22, v104 offset:1056
	v_mul_f32_e32 v105, 0x42000000, v105
	v_mul_f32_e32 v105, v105, v113
	ds_write_b32 v22, v105 offset:1320
	v_mul_f32_e32 v106, 0x42000000, v106
	v_mul_f32_e32 v106, v106, v114
	ds_write_b32 v22, v106 offset:1584
	v_mul_f32_e32 v107, 0x42000000, v107
	v_mul_f32_e32 v107, v107, v115
	ds_write_b32 v22, v107 offset:1848
	s_add_u32 s26, s26, 0x30000
	s_addc_u32 s27, s27, 0
	s_add_u32 s8, s8, 64
	s_addc_u32 s9, s9, 0
	s_cmp_lg_u32 s26, 0xc0000
	v_add_u32_e32 v22, 0x840, v22
	s_cbranch_scc1 .Lp0_qb_fast
	s_branch .LBB0_75
.Lp0_qb_slow:
	v_lshl_add_u64 v[20:21], v[18:19], 0, s[26:27]
	global_load_dword v20, v[20:21], off nt
	v_cndmask_b32_e64 v21, 0, 1, s[36:37]
	v_cmp_ne_u32_e64 s[6:7], 1, v21
	s_andn2_b64 vcc, exec, s[36:37]
	s_waitcnt vmcnt(0)
	v_mul_f32_e32 v20, 0x42000000, v20
	s_cbranch_vccnz .LBB0_61
	v_lshl_add_u64 v[24:25], s[8:9], 0, v[34:35]
	global_load_dword v21, v[24:25], off nt
	s_waitcnt vmcnt(0)
	v_mul_f32_e32 v20, v20, v21
.LBB0_61:
	v_lshl_add_u64 v[24:25], v[16:17], 0, s[26:27]
	global_load_dword v21, v[24:25], off nt
	ds_write_b32 v22, v20
	s_and_b64 vcc, exec, s[6:7]
	s_waitcnt vmcnt(0)
	v_mul_f32_e32 v23, 0x42000000, v21
	v_lshl_add_u64 v[20:21], s[8:9], 0, v[4:5]
	s_cbranch_vccnz .LBB0_63
	global_load_dword v24, v[20:21], off offset:8
	s_waitcnt vmcnt(0)
	v_mul_f32_e32 v23, v23, v24
.LBB0_63:
	v_lshl_add_u64 v[24:25], v[14:15], 0, s[26:27]
	global_load_dword v24, v[24:25], off nt
	ds_write_b32 v22, v23 offset:264
	s_and_b64 vcc, exec, s[6:7]
	s_waitcnt vmcnt(0)
	v_mul_f32_e32 v23, 0x42000000, v24
	s_cbranch_vccnz .LBB0_65
	global_load_dword v24, v[20:21], off offset:16
	s_waitcnt vmcnt(0)
	v_mul_f32_e32 v23, v23, v24
.LBB0_65:
	v_lshl_add_u64 v[24:25], v[12:13], 0, s[26:27]
	global_load_dword v24, v[24:25], off nt
	ds_write_b32 v22, v23 offset:528
	s_and_b64 vcc, exec, s[6:7]
	s_waitcnt vmcnt(0)
	v_mul_f32_e32 v23, 0x42000000, v24
	s_cbranch_vccnz .LBB0_67
	global_load_dword v24, v[20:21], off offset:24
	s_waitcnt vmcnt(0)
	v_mul_f32_e32 v23, v23, v24
.LBB0_67:
	v_lshl_add_u64 v[24:25], v[10:11], 0, s[26:27]
	global_load_dword v24, v[24:25], off nt
	ds_write_b32 v22, v23 offset:792
	s_and_b64 vcc, exec, s[6:7]
	s_waitcnt vmcnt(0)
	v_mul_f32_e32 v23, 0x42000000, v24
	s_cbranch_vccnz .LBB0_69
	global_load_dword v24, v[20:21], off offset:32
	s_waitcnt vmcnt(0)
	v_mul_f32_e32 v23, v23, v24
.LBB0_69:
	v_lshl_add_u64 v[24:25], v[8:9], 0, s[26:27]
	global_load_dword v24, v[24:25], off nt
	ds_write_b32 v22, v23 offset:1056
	s_and_b64 vcc, exec, s[6:7]
	s_waitcnt vmcnt(0)
	v_mul_f32_e32 v23, 0x42000000, v24
	s_cbranch_vccnz .LBB0_71
	global_load_dword v24, v[20:21], off offset:40
	s_waitcnt vmcnt(0)
	v_mul_f32_e32 v23, v23, v24
.LBB0_71:
	v_lshl_add_u64 v[24:25], v[6:7], 0, s[26:27]
	global_load_dword v24, v[24:25], off nt
	ds_write_b32 v22, v23 offset:1320
	s_and_b64 vcc, exec, s[6:7]
	s_waitcnt vmcnt(0)
	v_mul_f32_e32 v23, 0x42000000, v24
	s_cbranch_vccnz .LBB0_73
	global_load_dword v24, v[20:21], off offset:48
	s_waitcnt vmcnt(0)
	v_mul_f32_e32 v23, v23, v24
.LBB0_73:
	v_lshl_add_u64 v[24:25], v[2:3], 0, s[26:27]
	global_load_dword v24, v[24:25], off nt
	ds_write_b32 v22, v23 offset:1584
	s_and_b64 vcc, exec, s[6:7]
	s_waitcnt vmcnt(0)
	v_mul_f32_e32 v23, 0x42000000, v24
	s_cbranch_vccnz .LBB0_58
	global_load_dword v20, v[20:21], off offset:56
	s_waitcnt vmcnt(0)
	v_mul_f32_e32 v23, v23, v20
	s_branch .LBB0_58

.LBB0_80:
	s_lshl_b32 s36, s7, 1
	s_lshl_b32 s37, s9, 1
	s_add_i32 s44, s36, 4
	s_add_i32 s45, s37, 4
	s_add_i32 s47, s36, 8
	s_add_i32 s49, s37, 8
	s_add_i32 s50, s36, 12
	s_add_i32 s51, s37, 12
	v_or_b32_e32 v8, s36, v3
	v_or_b32_e32 v6, s37, v2
	s_add_i32 s52, s36, 16
	s_add_i32 s53, s37, 16
	s_add_i32 s54, s36, 20
	s_add_i32 s55, s37, 20
	s_add_i32 s56, s36, 24
	s_add_i32 s57, s37, 24
	s_add_i32 s58, s36, 28
	s_add_i32 s59, s37, 28
	v_or_b32_e32 v12, s44, v3
	v_or_b32_e32 v10, s45, v2
	v_or_b32_e32 v16, s47, v3
	v_or_b32_e32 v14, s49, v2
	v_or_b32_e32 v20, s50, v3
	v_or_b32_e32 v18, s51, v2
	v_mad_i64_i32 v[6:7], s[26:27], v6, s46, v[4:5]
	v_mad_i64_i32 v[8:9], s[26:27], v8, s46, v[4:5]
	v_or_b32_e32 v24, s52, v3
	v_or_b32_e32 v22, s53, v2
	v_or_b32_e32 v28, s54, v3
	v_or_b32_e32 v26, s55, v2
	v_or_b32_e32 v32, s56, v3
	v_or_b32_e32 v30, s57, v2
	v_or_b32_e32 v34, s58, v3
	v_or_b32_e32 v61, s59, v2
	v_mad_i64_i32 v[10:11], s[26:27], v10, s46, v[4:5]
	v_mad_i64_i32 v[12:13], s[26:27], v12, s46, v[4:5]
	v_mad_i64_i32 v[14:15], s[26:27], v14, s46, v[4:5]
	v_mad_i64_i32 v[16:17], s[26:27], v16, s46, v[4:5]
	v_mad_i64_i32 v[18:19], s[26:27], v18, s46, v[4:5]
	v_mad_i64_i32 v[20:21], s[26:27], v20, s46, v[4:5]
	v_mad_i64_i32 v[22:23], s[26:27], v22, s46, v[4:5]
	v_mad_i64_i32 v[24:25], s[26:27], v24, s46, v[4:5]
	v_mad_i64_i32 v[26:27], s[26:27], v26, s46, v[4:5]
	v_mad_i64_i32 v[28:29], s[26:27], v28, s46, v[4:5]
	v_mad_i64_i32 v[30:31], s[26:27], v30, s46, v[4:5]
	v_mad_i64_i32 v[32:33], s[26:27], v32, s46, v[4:5]
	v_mad_i64_i32 v[80:81], s[26:27], v61, s46, v[4:5]
	v_mad_i64_i32 v[82:83], s[26:27], v34, s46, v[4:5]
	global_load_dword v6, v[6:7], off nt
	s_nop 0
	global_load_dword v7, v[8:9], off nt
	s_nop 0
	global_load_dword v8, v[10:11], off nt
	global_load_dword v9, v[12:13], off nt
	s_nop 0
	global_load_dword v10, v[14:15], off nt
	global_load_dword v11, v[16:17], off nt
	global_load_dword v12, v[18:19], off nt
	global_load_dword v13, v[20:21], off nt
	s_nop 0
	global_load_dword v14, v[22:23], off nt
	global_load_dword v15, v[24:25], off nt
	global_load_dword v16, v[26:27], off nt
	global_load_dword v17, v[28:29], off nt
	global_load_dword v18, v[30:31], off nt
	global_load_dword v19, v[32:33], off nt
	global_load_dword v20, v[80:81], off nt
	global_load_dword v21, v[82:83], off nt
	v_or_b32_e32 v24, s36, v1
	v_or_b32_e32 v22, s37, v38
	v_mad_u64_u32 v[24:25], s[26:27], v24, s21, v[44:45]
	s_add_i32 s9, s9, 16
	s_add_i32 s7, s7, 16
	s_add_i32 s16, s16, -16
	v_mad_u64_u32 v[22:23], s[26:27], v22, s21, v[44:45]
	v_or_b32_e32 v25, s45, v38
	v_or_b32_e32 v23, s44, v1
	v_or_b32_e32 v32, s47, v1
	v_or_b32_e32 v30, s49, v38
	v_or_b32_e32 v34, s50, v1
	v_or_b32_e32 v61, s51, v38
	v_or_b32_e32 v79, s52, v1
	v_or_b32_e32 v84, s53, v38
	v_or_b32_e32 v90, s54, v1
	v_or_b32_e32 v88, s55, v38
	v_or_b32_e32 v94, s56, v1
	v_or_b32_e32 v92, s57, v38
	v_or_b32_e32 v98, s58, v1
	v_or_b32_e32 v96, s59, v38
	s_cmp_lg_u32 s16, 0
	v_mad_u64_u32 v[26:27], s[26:27], v25, s21, v[44:45]
	v_mad_u64_u32 v[28:29], s[26:27], v23, s21, v[44:45]
	v_mad_u64_u32 v[30:31], s[26:27], v30, s21, v[44:45]
	v_mad_u64_u32 v[32:33], s[26:27], v32, s21, v[44:45]
	v_mad_u64_u32 v[80:81], s[26:27], v61, s21, v[44:45]
	v_mad_u64_u32 v[82:83], s[26:27], v34, s21, v[44:45]
	v_mad_u64_u32 v[84:85], s[26:27], v84, s21, v[44:45]
	v_mad_u64_u32 v[86:87], s[26:27], v79, s21, v[44:45]
	v_mad_u64_u32 v[88:89], s[26:27], v88, s21, v[44:45]
	v_mad_u64_u32 v[90:91], s[26:27], v90, s21, v[44:45]
	v_mad_u64_u32 v[92:93], s[26:27], v92, s21, v[44:45]
	v_mad_u64_u32 v[94:95], s[26:27], v94, s21, v[44:45]
	v_mad_u64_u32 v[96:97], s[26:27], v96, s21, v[44:45]
	v_mad_u64_u32 v[98:99], s[26:27], v98, s21, v[44:45]
	s_waitcnt vmcnt(14)
	v_pk_mul_f32 v[6:7], v[6:7], s[24:25] op_sel_hi:[1,0]
	ds_write_b32 v22, v6
	ds_write_b32 v24, v7
	s_waitcnt vmcnt(12)
	v_pk_mul_f32 v[6:7], v[8:9], s[24:25] op_sel_hi:[1,0]
	s_waitcnt vmcnt(10)
	v_pk_mul_f32 v[8:9], v[10:11], s[24:25] op_sel_hi:[1,0]
	s_waitcnt vmcnt(8)
	v_pk_mul_f32 v[10:11], v[12:13], s[24:25] op_sel_hi:[1,0]
	s_waitcnt vmcnt(6)
	v_pk_mul_f32 v[12:13], v[14:15], s[24:25] op_sel_hi:[1,0]
	s_waitcnt vmcnt(4)
	v_pk_mul_f32 v[14:15], v[16:17], s[24:25] op_sel_hi:[1,0]
	s_waitcnt vmcnt(2)
	v_pk_mul_f32 v[16:17], v[18:19], s[24:25] op_sel_hi:[1,0]
	s_waitcnt vmcnt(0)
	v_pk_mul_f32 v[18:19], v[20:21], s[24:25] op_sel_hi:[1,0]
	ds_write_b32 v26, v6
	ds_write_b32 v28, v7
	ds_write_b32 v30, v8
	ds_write_b32 v32, v9
	ds_write_b32 v80, v10
	ds_write_b32 v82, v11
	ds_write_b32 v84, v12
	ds_write_b32 v86, v13
	ds_write_b32 v88, v14
	ds_write_b32 v90, v15
	ds_write_b32 v92, v16
	ds_write_b32 v94, v17
	ds_write_b32 v96, v18
	ds_write_b32 v98, v19
	s_cbranch_scc1 .LBB0_80
	s_waitcnt lgkmcnt(0)
	ds_read2_b32 v[8:9], v59 offset1:16
	ds_read2_b32 v[10:11], v59 offset0:33 offset1:49
	ds_read2_b32 v[12:13], v59 offset0:66 offset1:82
	ds_read2_b32 v[14:15], v59 offset0:99 offset1:115
	ds_read2_b32 v[18:19], v59 offset0:132 offset1:148
	ds_read2_b32 v[20:21], v59 offset0:165 offset1:181
	ds_read2_b32 v[22:23], v59 offset0:198 offset1:214
	ds_read2_b32 v[24:25], v59 offset0:231 offset1:247
	s_waitcnt lgkmcnt(7)
	v_max_f32_e32 v4, v8, v8
	s_waitcnt lgkmcnt(6)
	v_max_f32_e32 v5, v10, v10
	v_med3_f32 v8, v4, s39, v77
	v_med3_f32 v5, v5, s39, v77
	v_mov_b32_e32 v4, v35
	v_cvt_pk_fp8_f32 v4, v8, v5
	s_waitcnt lgkmcnt(5)
	v_max_f32_e32 v6, v12, v12
	s_waitcnt lgkmcnt(4)
	v_max_f32_e32 v7, v14, v14
	v_med3_f32 v6, v6, s39, v77
	v_med3_f32 v7, v7, s39, v77
	v_cvt_pk_fp8_f32 v4, v6, v7 op_sel:[0,0,1]
	s_waitcnt lgkmcnt(3)
	v_max_f32_e32 v5, v18, v18
	s_waitcnt lgkmcnt(2)
	v_max_f32_e32 v6, v20, v20
	v_med3_f32 v10, v5, s39, v77
	v_med3_f32 v6, v6, s39, v77
	v_mov_b32_e32 v5, v35
	v_cvt_pk_fp8_f32 v5, v10, v6
	v_add_u32_e32 v10, 0x400, v59
	ds_read2_b32 v[26:27], v10 offset0:8 offset1:24
	ds_read2_b32 v[28:29], v10 offset0:41 offset1:57
	ds_read2_b32 v[30:31], v10 offset0:74 offset1:90
	ds_read2_b32 v[32:33], v10 offset0:107 offset1:123
	s_waitcnt lgkmcnt(5)
	v_max_f32_e32 v7, v22, v22
	s_waitcnt lgkmcnt(4)
	v_max_f32_e32 v8, v24, v24
	v_med3_f32 v7, v7, s39, v77
	v_med3_f32 v8, v8, s39, v77
	v_cvt_pk_fp8_f32 v5, v7, v8 op_sel:[0,0,1]
	s_waitcnt lgkmcnt(3)
	v_max_f32_e32 v6, v26, v26
	s_waitcnt lgkmcnt(2)
	v_max_f32_e32 v7, v28, v28
	v_med3_f32 v14, v6, s39, v77
	v_med3_f32 v7, v7, s39, v77
	v_mov_b32_e32 v6, v35
	v_cvt_pk_fp8_f32 v6, v14, v7
	ds_read2_b32 v[80:81], v10 offset0:140 offset1:156
	ds_read2_b32 v[82:83], v10 offset0:173 offset1:189
	ds_read2_b32 v[84:85], v10 offset0:206 offset1:222
	s_waitcnt lgkmcnt(4)
	v_max_f32_e32 v8, v30, v30
	s_waitcnt lgkmcnt(3)
	v_max_f32_e32 v12, v32, v32
	v_med3_f32 v8, v8, s39, v77
	v_med3_f32 v7, v12, s39, v77
	ds_read2_b32 v[86:87], v10 offset0:239 offset1:255
	v_cvt_pk_fp8_f32 v6, v8, v7 op_sel:[0,0,1]
	s_waitcnt lgkmcnt(3)
	v_max_f32_e32 v7, v80, v80
	s_waitcnt lgkmcnt(2)
	v_max_f32_e32 v8, v82, v82
	v_med3_f32 v10, v7, s39, v77
	v_med3_f32 v8, v8, s39, v77
	v_mov_b32_e32 v7, v35
	v_cvt_pk_fp8_f32 v7, v10, v8
	s_waitcnt lgkmcnt(1)
	v_max_f32_e32 v12, v84, v84
	s_waitcnt lgkmcnt(0)
	v_max_f32_e32 v8, v86, v86
	v_med3_f32 v10, v12, s39, v77
	v_med3_f32 v8, v8, s39, v77
	v_cvt_pk_fp8_f32 v7, v10, v8 op_sel:[0,0,1]
	s_ashr_i32 s9, s8, 31
	v_or_b32_e32 v34, s6, v45
	v_lshl_add_u64 v[16:17], v[54:55], 0, s[8:9]
	v_lshlrev_b64 v[88:89], 12, v[34:35]
	v_lshl_add_u64 v[88:89], v[16:17], 0, v[88:89]
	global_store_dwordx4 v[88:89], v[4:7], off
	v_or_b32_e32 v34, s6, v62
	s_mov_b64 s[26:27], 0
	v_max_f32_e32 v4, v9, v9
	v_max_f32_e32 v5, v11, v11
	v_med3_f32 v7, v4, s39, v77
	v_med3_f32 v5, v5, s39, v77
	v_mov_b32_e32 v4, v35
	v_cvt_pk_fp8_f32 v4, v7, v5
	v_max_f32_e32 v6, v13, v13
	v_max_f32_e32 v5, v15, v15
	v_med3_f32 v6, v6, s39, v77
	v_med3_f32 v5, v5, s39, v77
	v_cvt_pk_fp8_f32 v4, v6, v5 op_sel:[0,0,1]
	v_max_f32_e32 v5, v19, v19
	v_max_f32_e32 v6, v21, v21
	v_med3_f32 v8, v5, s39, v77
	v_med3_f32 v6, v6, s39, v77
	v_mov_b32_e32 v5, v35
	v_cvt_pk_fp8_f32 v5, v8, v6
	v_max_f32_e32 v7, v23, v23
	v_max_f32_e32 v6, v25, v25
	v_med3_f32 v7, v7, s39, v77
	v_med3_f32 v6, v6, s39, v77
	v_cvt_pk_fp8_f32 v5, v7, v6 op_sel:[0,0,1]
	v_max_f32_e32 v6, v27, v27
	v_max_f32_e32 v7, v29, v29
	v_med3_f32 v9, v6, s39, v77
	v_med3_f32 v7, v7, s39, v77
	v_mov_b32_e32 v6, v35
	v_cvt_pk_fp8_f32 v6, v9, v7
	v_max_f32_e32 v8, v31, v31
	v_max_f32_e32 v7, v33, v33
	v_med3_f32 v8, v8, s39, v77
	v_med3_f32 v7, v7, s39, v77
	v_cvt_pk_fp8_f32 v6, v8, v7 op_sel:[0,0,1]
	v_max_f32_e32 v7, v81, v81
	v_max_f32_e32 v8, v83, v83
	v_med3_f32 v10, v7, s39, v77
	v_med3_f32 v8, v8, s39, v77
	v_mov_b32_e32 v7, v35
	v_cvt_pk_fp8_f32 v7, v10, v8
	v_max_f32_e32 v9, v85, v85
	v_max_f32_e32 v8, v87, v87
	v_med3_f32 v9, v9, s39, v77
	v_med3_f32 v8, v8, s39, v77
	v_cvt_pk_fp8_f32 v7, v9, v8 op_sel:[0,0,1]
	v_lshlrev_b64 v[8:9], 12, v[34:35]
	v_lshl_add_u64 v[8:9], v[16:17], 0, v[8:9]
	global_store_dwordx4 v[8:9], v[4:7], off
	s_waitcnt lgkmcnt(0)

.LBB0_84:
	s_lshl_b32 s11, s7, 1
	s_lshl_b32 s16, s9, 1
	v_or_b32_e32 v6, s16, v2
	s_add_i32 s36, s11, 4
	s_add_i32 s37, s16, 4
	s_add_i32 s44, s11, 8
	s_add_i32 s45, s16, 8
	s_add_i32 s47, s11, 12
	s_add_i32 s49, s16, 12
	s_add_i32 s50, s11, 16
	s_add_i32 s51, s16, 16
	s_add_i32 s52, s11, 20
	s_add_i32 s53, s16, 20
	s_add_i32 s54, s11, 24
	s_add_i32 s55, s16, 24
	s_add_i32 s56, s11, 28
	s_add_i32 s57, s16, 28
	v_or_b32_e32 v8, s11, v3
	v_mad_i64_i32 v[6:7], s[26:27], v6, s46, v[4:5]
	v_or_b32_e32 v12, s36, v3
	v_or_b32_e32 v10, s37, v2
	v_or_b32_e32 v16, s44, v3
	v_or_b32_e32 v14, s45, v2
	v_or_b32_e32 v20, s47, v3
	v_or_b32_e32 v18, s49, v2
	v_or_b32_e32 v24, s50, v3
	v_or_b32_e32 v22, s51, v2
	v_or_b32_e32 v28, s52, v3
	v_or_b32_e32 v26, s53, v2
	v_or_b32_e32 v32, s54, v3
	v_or_b32_e32 v30, s55, v2
	v_or_b32_e32 v34, s56, v3
	v_or_b32_e32 v61, s57, v2
	v_mad_i64_i32 v[8:9], s[26:27], v8, s46, v[4:5]
	v_mad_i64_i32 v[10:11], s[26:27], v10, s46, v[4:5]
	v_mad_i64_i32 v[12:13], s[26:27], v12, s46, v[4:5]
	v_mad_i64_i32 v[14:15], s[26:27], v14, s46, v[4:5]
	v_mad_i64_i32 v[16:17], s[26:27], v16, s46, v[4:5]
	v_mad_i64_i32 v[18:19], s[26:27], v18, s46, v[4:5]
	v_mad_i64_i32 v[20:21], s[26:27], v20, s46, v[4:5]
	v_mad_i64_i32 v[22:23], s[26:27], v22, s46, v[4:5]
	v_mad_i64_i32 v[24:25], s[26:27], v24, s46, v[4:5]
	v_mad_i64_i32 v[26:27], s[26:27], v26, s46, v[4:5]
	v_mad_i64_i32 v[28:29], s[26:27], v28, s46, v[4:5]
	v_mad_i64_i32 v[30:31], s[26:27], v30, s46, v[4:5]
	v_mad_i64_i32 v[32:33], s[26:27], v32, s46, v[4:5]
	v_mad_i64_i32 v[80:81], s[26:27], v61, s46, v[4:5]
	v_mad_i64_i32 v[82:83], s[26:27], v34, s46, v[4:5]
	global_load_dword v34, v[6:7], off nt
	global_load_dword v61, v[8:9], off nt
	global_load_dword v79, v[10:11], off nt
	global_load_dword v84, v[12:13], off nt
	global_load_dword v85, v[14:15], off nt
	global_load_dword v86, v[16:17], off nt
	global_load_dword v87, v[18:19], off nt
	global_load_dword v88, v[20:21], off nt
	global_load_dword v89, v[22:23], off nt
	global_load_dword v90, v[24:25], off nt
	global_load_dword v91, v[26:27], off nt
	global_load_dword v92, v[28:29], off nt
	global_load_dword v93, v[30:31], off nt
	global_load_dword v94, v[32:33], off nt
	global_load_dword v95, v[80:81], off nt
	global_load_dword v96, v[82:83], off nt
	v_or_b32_e32 v8, s11, v1
	v_or_b32_e32 v6, s16, v38
	s_add_i32 s9, s9, 16
	s_add_i32 s7, s7, 16
	s_add_i32 s10, s10, -16
	v_mad_u64_u32 v[6:7], s[26:27], v6, s21, v[44:45]
	v_mad_u64_u32 v[8:9], s[26:27], v8, s21, v[44:45]
	v_or_b32_e32 v7, s36, v1
	v_or_b32_e32 v9, s37, v38
	v_or_b32_e32 v16, s44, v1
	v_or_b32_e32 v14, s45, v38
	v_or_b32_e32 v20, s47, v1
	v_or_b32_e32 v18, s49, v38
	v_or_b32_e32 v24, s50, v1
	v_or_b32_e32 v22, s51, v38
	v_or_b32_e32 v28, s52, v1
	v_or_b32_e32 v26, s53, v38
	v_or_b32_e32 v32, s54, v1
	v_or_b32_e32 v30, s55, v38
	v_or_b32_e32 v82, s56, v1
	v_or_b32_e32 v80, s57, v38
	s_cmp_lg_u32 s10, 0
	v_mad_u64_u32 v[10:11], s[26:27], v9, s21, v[44:45]
	v_mad_u64_u32 v[12:13], s[26:27], v7, s21, v[44:45]
	v_mad_u64_u32 v[14:15], s[26:27], v14, s21, v[44:45]
	v_mad_u64_u32 v[16:17], s[26:27], v16, s21, v[44:45]
	v_mad_u64_u32 v[18:19], s[26:27], v18, s21, v[44:45]
	v_mad_u64_u32 v[20:21], s[26:27], v20, s21, v[44:45]
	v_mad_u64_u32 v[22:23], s[26:27], v22, s21, v[44:45]
	v_mad_u64_u32 v[24:25], s[26:27], v24, s21, v[44:45]
	v_mad_u64_u32 v[26:27], s[26:27], v26, s21, v[44:45]
	v_mad_u64_u32 v[28:29], s[26:27], v28, s21, v[44:45]
	v_mad_u64_u32 v[30:31], s[26:27], v30, s21, v[44:45]
	v_mad_u64_u32 v[32:33], s[26:27], v32, s21, v[44:45]
	v_mad_u64_u32 v[80:81], s[26:27], v80, s21, v[44:45]
	v_mad_u64_u32 v[82:83], s[26:27], v82, s21, v[44:45]
	s_waitcnt vmcnt(15)
	ds_write_b32 v6, v34
	s_waitcnt vmcnt(14)
	ds_write_b32 v8, v61
	s_waitcnt vmcnt(13)
	ds_write_b32 v10, v79
	s_waitcnt vmcnt(12)
	ds_write_b32 v12, v84
	s_waitcnt vmcnt(11)
	ds_write_b32 v14, v85
	s_waitcnt vmcnt(10)
	ds_write_b32 v16, v86
	s_waitcnt vmcnt(9)
	ds_write_b32 v18, v87
	s_waitcnt vmcnt(8)
	ds_write_b32 v20, v88
	s_waitcnt vmcnt(7)
	ds_write_b32 v22, v89
	s_waitcnt vmcnt(6)
	ds_write_b32 v24, v90
	s_waitcnt vmcnt(5)
	ds_write_b32 v26, v91
	s_waitcnt vmcnt(4)
	ds_write_b32 v28, v92
	s_waitcnt vmcnt(3)
	ds_write_b32 v30, v93
	s_waitcnt vmcnt(2)
	ds_write_b32 v32, v94
	s_waitcnt vmcnt(1)
	ds_write_b32 v80, v95
	s_waitcnt vmcnt(0)
	ds_write_b32 v82, v96
	s_cbranch_scc1 .LBB0_84
	s_waitcnt lgkmcnt(0)
	ds_read2_b32 v[6:7], v65 offset1:8
	ds_read2_b32 v[10:11], v65 offset0:33 offset1:41
	ds_read2_b32 v[12:13], v65 offset0:66 offset1:74
	ds_read2_b32 v[14:15], v65 offset0:99 offset1:107
	ds_read2_b32 v[16:17], v65 offset0:132 offset1:140
	ds_read2_b32 v[18:19], v65 offset0:165 offset1:173
	s_waitcnt lgkmcnt(5)
	v_bfe_u32 v2, v6, 16, 1
	v_add3_u32 v2, v6, v2, s41
	s_waitcnt lgkmcnt(4)
	v_bfe_u32 v3, v10, 16, 1
	v_lshrrev_b32_e32 v2, 16, v2
	v_add3_u32 v3, v10, v3, s41
	v_and_or_b32 v2, v3, s42, v2
	s_waitcnt lgkmcnt(3)
	v_bfe_u32 v3, v12, 16, 1
	v_add3_u32 v3, v12, v3, s41
	s_waitcnt lgkmcnt(2)
	v_bfe_u32 v4, v14, 16, 1
	ds_read2_b32 v[20:21], v65 offset0:198 offset1:206
	v_lshrrev_b32_e32 v3, 16, v3
	v_add3_u32 v4, v14, v4, s41
	ds_read2_b32 v[22:23], v65 offset0:231 offset1:239
	v_and_or_b32 v3, v4, s42, v3
	s_waitcnt lgkmcnt(3)
	v_bfe_u32 v4, v16, 16, 1
	v_add3_u32 v4, v16, v4, s41
	s_waitcnt lgkmcnt(2)
	v_bfe_u32 v5, v18, 16, 1
	v_lshrrev_b32_e32 v4, 16, v4
	v_add3_u32 v5, v18, v5, s41
	v_and_or_b32 v4, v5, s42, v4
	s_waitcnt lgkmcnt(1)
	v_bfe_u32 v5, v20, 16, 1
	v_or_b32_e32 v24, s6, v64
	s_ashr_i32 s9, s8, 31
	v_add3_u32 v5, v20, v5, s41
	s_waitcnt lgkmcnt(0)
	v_bfe_u32 v6, v22, 16, 1
	v_ashrrev_i32_e32 v25, 31, v24
	v_lshl_add_u64 v[8:9], s[8:9], 1, v[56:57]
	v_lshrrev_b32_e32 v5, 16, v5
	v_add3_u32 v6, v22, v6, s41
	v_lshlrev_b64 v[24:25], 13, v[24:25]
	v_and_or_b32 v5, v6, s42, v5
	v_lshl_add_u64 v[24:25], v[8:9], 0, v[24:25]
	global_store_dwordx4 v[24:25], v[2:5], off
	v_bfe_u32 v6, v23, 16, 1
	v_add3_u32 v6, v23, v6, s41
	v_bfe_u32 v2, v7, 16, 1
	v_add3_u32 v2, v7, v2, s41
	v_bfe_u32 v3, v11, 16, 1
	v_lshrrev_b32_e32 v2, 16, v2
	v_add3_u32 v3, v11, v3, s41
	v_and_or_b32 v2, v3, s42, v2
	v_bfe_u32 v3, v13, 16, 1
	v_add3_u32 v3, v13, v3, s41
	v_bfe_u32 v4, v15, 16, 1
	v_lshrrev_b32_e32 v3, 16, v3
	v_add3_u32 v4, v15, v4, s41
	v_and_or_b32 v3, v4, s42, v3
	v_bfe_u32 v4, v17, 16, 1
	v_add3_u32 v4, v17, v4, s41
	v_bfe_u32 v5, v19, 16, 1
	v_lshrrev_b32_e32 v4, 16, v4
	v_add3_u32 v5, v19, v5, s41
	v_and_or_b32 v4, v5, s42, v4
	v_bfe_u32 v5, v21, 16, 1
	v_add3_u32 v5, v21, v5, s41
	v_lshrrev_b32_e32 v5, 16, v5
	v_and_or_b32 v5, v6, s42, v5
	v_or_b32_e32 v6, s6, v66
	v_ashrrev_i32_e32 v7, 31, v6
	v_lshlrev_b64 v[6:7], 13, v[6:7]
	ds_read2_b32 v[10:11], v65 offset0:16 offset1:24
	v_lshl_add_u64 v[6:7], v[8:9], 0, v[6:7]
	global_store_dwordx4 v[6:7], v[2:5], off
	ds_read2_b32 v[6:7], v65 offset0:49 offset1:57
	ds_read2_b32 v[12:13], v65 offset0:82 offset1:90
	ds_read2_b32 v[14:15], v65 offset0:115 offset1:123
	s_waitcnt lgkmcnt(3)
	v_bfe_u32 v2, v10, 16, 1
	v_add3_u32 v2, v10, v2, s41
	s_waitcnt lgkmcnt(2)
	v_bfe_u32 v3, v6, 16, 1
	ds_read2_b32 v[16:17], v65 offset0:148 offset1:156
	v_lshrrev_b32_e32 v2, 16, v2
	v_add3_u32 v3, v6, v3, s41
	ds_read2_b32 v[18:19], v65 offset0:181 offset1:189
	v_and_or_b32 v2, v3, s42, v2
	s_waitcnt lgkmcnt(3)
	v_bfe_u32 v3, v12, 16, 1
	v_add3_u32 v3, v12, v3, s41
	s_waitcnt lgkmcnt(2)
	v_bfe_u32 v4, v14, 16, 1
	ds_read2_b32 v[20:21], v65 offset0:214 offset1:222
	v_lshrrev_b32_e32 v3, 16, v3
	v_add3_u32 v4, v14, v4, s41
	ds_read2_b32 v[22:23], v65 offset0:247 offset1:255
	v_and_or_b32 v3, v4, s42, v3
	s_waitcnt lgkmcnt(3)
	v_bfe_u32 v4, v16, 16, 1
	v_add3_u32 v4, v16, v4, s41
	s_waitcnt lgkmcnt(2)
	v_bfe_u32 v5, v18, 16, 1
	v_lshrrev_b32_e32 v4, 16, v4
	v_add3_u32 v5, v18, v5, s41
	v_and_or_b32 v4, v5, s42, v4
	s_waitcnt lgkmcnt(1)
	v_bfe_u32 v5, v20, 16, 1
	v_or_b32_e32 v24, s6, v67
	v_add3_u32 v5, v20, v5, s41
	s_waitcnt lgkmcnt(0)
	v_bfe_u32 v6, v22, 16, 1
	v_ashrrev_i32_e32 v25, 31, v24
	v_lshrrev_b32_e32 v5, 16, v5
	v_add3_u32 v6, v22, v6, s41
	v_lshlrev_b64 v[24:25], 13, v[24:25]
	v_and_or_b32 v5, v6, s42, v5
	v_lshl_add_u64 v[24:25], v[8:9], 0, v[24:25]
	global_store_dwordx4 v[24:25], v[2:5], off
	v_bfe_u32 v6, v23, 16, 1
	v_add3_u32 v6, v23, v6, s41
	v_bfe_u32 v2, v11, 16, 1
	v_add3_u32 v2, v11, v2, s41
	v_bfe_u32 v3, v7, 16, 1
	v_lshrrev_b32_e32 v2, 16, v2
	v_add3_u32 v3, v7, v3, s41
	v_and_or_b32 v2, v3, s42, v2
	v_bfe_u32 v3, v13, 16, 1
	v_add3_u32 v3, v13, v3, s41
	v_bfe_u32 v4, v15, 16, 1
	v_lshrrev_b32_e32 v3, 16, v3
	v_add3_u32 v4, v15, v4, s41
	v_and_or_b32 v3, v4, s42, v3
	v_bfe_u32 v4, v17, 16, 1
	v_add3_u32 v4, v17, v4, s41
	v_bfe_u32 v5, v19, 16, 1
	v_lshrrev_b32_e32 v4, 16, v4
	v_add3_u32 v5, v19, v5, s41
	v_and_or_b32 v4, v5, s42, v4
	v_bfe_u32 v5, v21, 16, 1
	v_add3_u32 v5, v21, v5, s41
	v_lshrrev_b32_e32 v5, 16, v5
	v_and_or_b32 v5, v6, s42, v5
	v_or_b32_e32 v6, s6, v68
	v_ashrrev_i32_e32 v7, 31, v6
	v_lshlrev_b64 v[6:7], 13, v[6:7]
	v_lshl_add_u64 v[6:7], v[8:9], 0, v[6:7]
	global_store_dwordx4 v[6:7], v[2:5], off
	s_waitcnt lgkmcnt(0)
	s_branch .LBB0_11
